# scan waves: y stored by one lane per row pair (exec-masked ds_write), eight-way same-address LDS write avoided
# baseline (speedup 1.0000x reference)
.LBB0_390:
	s_and_b32 s3, s2, 1
	s_mul_i32 s8, s3, 0x5000
	v_add_u32_e32 v2, s8, v136
	s_mul_i32 s8, s2, 0xab
	s_bfe_u32 s8, s8, 0x70009
	s_mul_i32 s8, s8, 3
	s_sub_i32 s8, s2, s8
	s_and_b32 s8, s8, 0xff
	s_mulk_i32 s8, 0x1100
	v_add_u32_e32 v3, s8, v137
	v_lshl_add_u32 v1, s3, 12, v137
	ds_read_b128 v[176:179], v2 offset:4096
	ds_read_b128 v[180:183], v2 offset:4112
	ds_read_b128 v[200:203], v2 offset:12288
	ds_read_b128 v[204:207], v2 offset:12304
	ds_read_b64 v[216:217], v3 offset:40960
	ds_read_b128 v[184:187], v2 offset:0
	ds_read_b128 v[188:191], v2 offset:16
	ds_read_b128 v[192:195], v2 offset:8192
	ds_read_b128 v[196:199], v2 offset:8208
	s_waitcnt lgkmcnt(0)
	v_pk_mul_f32 v[164:165], v[72:73], v[176:177]
	v_pk_mul_f32 v[166:167], v[80:81], v[176:177]
	ds_read_b128 v[208:211], v2 offset:16384
	v_pk_fma_f32 v[164:165], v[74:75], v[178:179], v[164:165]
	v_pk_fma_f32 v[166:167], v[82:83], v[178:179], v[166:167]
	ds_read_b128 v[212:215], v2 offset:16400
	v_pk_fma_f32 v[164:165], v[76:77], v[180:181], v[164:165]
	v_pk_fma_f32 v[166:167], v[84:85], v[180:181], v[166:167]
	ds_read_b128 v[4:7], v2 offset:4352
	v_pk_fma_f32 v[164:165], v[78:79], v[182:183], v[164:165]
	v_pk_fma_f32 v[166:167], v[86:87], v[182:183], v[166:167]
	ds_read_b128 v[8:11], v2 offset:4368
	v_pk_mul_f32 v[218:219], v[216:217], v[200:201] op_sel_hi:[0,1]
	v_pk_mul_f32 v[226:227], v[216:217], v[200:201] op_sel:[1,0]
	ds_read_b128 v[40:43], v2 offset:12544
	v_pk_mul_f32 v[220:221], v[216:217], v[202:203] op_sel_hi:[0,1]
	v_pk_mul_f32 v[228:229], v[216:217], v[202:203] op_sel:[1,0]
	ds_read_b128 v[44:47], v2 offset:12560
	v_pk_mul_f32 v[222:223], v[216:217], v[204:205] op_sel_hi:[0,1]
	v_pk_mul_f32 v[230:231], v[216:217], v[204:205] op_sel:[1,0]
	ds_read_b64 v[26:27], v3 offset:41216
	v_pk_mul_f32 v[224:225], v[216:217], v[206:207] op_sel_hi:[0,1]
	v_pk_mul_f32 v[234:235], v[216:217], v[206:207] op_sel:[1,0]
	ds_read_b128 v[12:15], v2 offset:256
	v_add_f32_e32 v172, v164, v165
	v_add_f32_e32 v174, v166, v167
	ds_read_b128 v[28:31], v2 offset:272
	v_pk_fma_f32 v[218:219], v[72:73], v[184:185], v[218:219]
	v_pk_fma_f32 v[226:227], v[80:81], v[184:185], v[226:227]
	ds_read_b128 v[32:35], v2 offset:8448
	v_pk_fma_f32 v[220:221], v[74:75], v[186:187], v[220:221]
	v_pk_fma_f32 v[228:229], v[82:83], v[186:187], v[228:229]
	ds_read_b128 v[36:39], v2 offset:8464
	v_add_f32_dpp v172, v172, v172 quad_perm:[1,0,3,2] row_mask:0xf bank_mask:0xf bound_ctrl:1
	v_add_f32_dpp v174, v174, v174 quad_perm:[1,0,3,2] row_mask:0xf bank_mask:0xf bound_ctrl:1
	v_pk_fma_f32 v[222:223], v[76:77], v[188:189], v[222:223]
	v_pk_fma_f32 v[230:231], v[84:85], v[188:189], v[230:231]
	v_pk_fma_f32 v[224:225], v[78:79], v[190:191], v[224:225]
	v_pk_fma_f32 v[234:235], v[86:87], v[190:191], v[234:235]
	v_add_f32_dpp v172, v172, v172 quad_perm:[2,3,0,1] row_mask:0xf bank_mask:0xf bound_ctrl:1
	v_add_f32_dpp v174, v174, v174 quad_perm:[2,3,0,1] row_mask:0xf bank_mask:0xf bound_ctrl:1
	s_nop 0
	v_add_f32_dpp v172, v172, v172 row_half_mirror row_mask:0xf bank_mask:0xf bound_ctrl:1
	v_add_f32_dpp v174, v174, v174 row_half_mirror row_mask:0xf bank_mask:0xf bound_ctrl:1
	v_pk_fma_f32 v[72:73], v[192:193], v[172:173], v[218:219] op_sel_hi:[1,0,1]
	v_pk_fma_f32 v[80:81], v[192:193], v[174:175], v[226:227] op_sel_hi:[1,0,1]
	v_pk_fma_f32 v[74:75], v[194:195], v[172:173], v[220:221] op_sel_hi:[1,0,1]
	v_pk_fma_f32 v[82:83], v[194:195], v[174:175], v[228:229] op_sel_hi:[1,0,1]
	v_pk_fma_f32 v[76:77], v[196:197], v[172:173], v[222:223] op_sel_hi:[1,0,1]
	v_pk_fma_f32 v[84:85], v[196:197], v[174:175], v[230:231] op_sel_hi:[1,0,1]
	v_pk_fma_f32 v[78:79], v[198:199], v[172:173], v[224:225] op_sel_hi:[1,0,1]
	v_pk_fma_f32 v[86:87], v[198:199], v[174:175], v[234:235] op_sel_hi:[1,0,1]
	s_waitcnt lgkmcnt(0)
	v_pk_mul_f32 v[164:165], v[72:73], v[4:5]
	v_pk_mul_f32 v[166:167], v[80:81], v[4:5]
	ds_read_b128 v[48:51], v2 offset:16640
	v_pk_mul_f32 v[168:169], v[72:73], v[208:209]
	v_pk_mul_f32 v[170:171], v[80:81], v[208:209]
	ds_read_b128 v[52:55], v2 offset:16656
	v_pk_fma_f32 v[164:165], v[74:75], v[6:7], v[164:165]
	v_pk_fma_f32 v[166:167], v[82:83], v[6:7], v[166:167]
	ds_read_b128 v[176:179], v2 offset:4608
	v_pk_fma_f32 v[168:169], v[74:75], v[210:211], v[168:169]
	v_pk_fma_f32 v[170:171], v[82:83], v[210:211], v[170:171]
	ds_read_b128 v[180:183], v2 offset:4624
	v_pk_fma_f32 v[164:165], v[76:77], v[8:9], v[164:165]
	v_pk_fma_f32 v[166:167], v[84:85], v[8:9], v[166:167]
	ds_read_b128 v[200:203], v2 offset:12800
	v_pk_fma_f32 v[168:169], v[76:77], v[212:213], v[168:169]
	v_pk_fma_f32 v[170:171], v[84:85], v[212:213], v[170:171]
	ds_read_b128 v[204:207], v2 offset:12816
	v_pk_fma_f32 v[164:165], v[78:79], v[10:11], v[164:165]
	v_pk_fma_f32 v[166:167], v[86:87], v[10:11], v[166:167]
	ds_read_b64 v[216:217], v3 offset:41472
	v_pk_fma_f32 v[168:169], v[78:79], v[214:215], v[168:169]
	v_pk_fma_f32 v[170:171], v[86:87], v[214:215], v[170:171]
	ds_read_b128 v[184:187], v2 offset:512
	v_pk_mul_f32 v[218:219], v[26:27], v[40:41] op_sel_hi:[0,1]
	v_pk_mul_f32 v[226:227], v[26:27], v[40:41] op_sel:[1,0]
	ds_read_b128 v[188:191], v2 offset:528
	v_pk_mul_f32 v[220:221], v[26:27], v[42:43] op_sel_hi:[0,1]
	v_pk_mul_f32 v[228:229], v[26:27], v[42:43] op_sel:[1,0]
	ds_read_b128 v[192:195], v2 offset:8704
	v_pk_mul_f32 v[222:223], v[26:27], v[44:45] op_sel_hi:[0,1]
	v_pk_mul_f32 v[230:231], v[26:27], v[44:45] op_sel:[1,0]
	ds_read_b128 v[196:199], v2 offset:8720
	v_pk_mul_f32 v[224:225], v[26:27], v[46:47] op_sel_hi:[0,1]
	v_pk_mul_f32 v[234:235], v[26:27], v[46:47] op_sel:[1,0]
	v_add_f32_e32 v172, v164, v165
	v_add_f32_e32 v174, v166, v167
	v_add_f32_e32 v160, v168, v169
	v_add_f32_e32 v161, v170, v171
	v_pk_fma_f32 v[218:219], v[72:73], v[12:13], v[218:219]
	v_pk_fma_f32 v[226:227], v[80:81], v[12:13], v[226:227]
	v_pk_fma_f32 v[220:221], v[74:75], v[14:15], v[220:221]
	v_pk_fma_f32 v[228:229], v[82:83], v[14:15], v[228:229]
	v_add_f32_dpp v172, v172, v172 quad_perm:[1,0,3,2] row_mask:0xf bank_mask:0xf bound_ctrl:1
	v_add_f32_dpp v174, v174, v174 quad_perm:[1,0,3,2] row_mask:0xf bank_mask:0xf bound_ctrl:1
	v_add_f32_dpp v160, v160, v160 quad_perm:[1,0,3,2] row_mask:0xf bank_mask:0xf bound_ctrl:1
	v_add_f32_dpp v161, v161, v161 quad_perm:[1,0,3,2] row_mask:0xf bank_mask:0xf bound_ctrl:1
	v_pk_fma_f32 v[222:223], v[76:77], v[28:29], v[222:223]
	v_pk_fma_f32 v[230:231], v[84:85], v[28:29], v[230:231]
	v_pk_fma_f32 v[224:225], v[78:79], v[30:31], v[224:225]
	v_pk_fma_f32 v[234:235], v[86:87], v[30:31], v[234:235]
	v_add_f32_dpp v172, v172, v172 quad_perm:[2,3,0,1] row_mask:0xf bank_mask:0xf bound_ctrl:1
	v_add_f32_dpp v174, v174, v174 quad_perm:[2,3,0,1] row_mask:0xf bank_mask:0xf bound_ctrl:1
	v_add_f32_dpp v160, v160, v160 quad_perm:[2,3,0,1] row_mask:0xf bank_mask:0xf bound_ctrl:1
	v_add_f32_dpp v161, v161, v161 quad_perm:[2,3,0,1] row_mask:0xf bank_mask:0xf bound_ctrl:1
	v_add_f32_dpp v172, v172, v172 row_half_mirror row_mask:0xf bank_mask:0xf bound_ctrl:1
	v_add_f32_dpp v174, v174, v174 row_half_mirror row_mask:0xf bank_mask:0xf bound_ctrl:1
	v_add_f32_dpp v160, v160, v160 row_half_mirror row_mask:0xf bank_mask:0xf bound_ctrl:1
	v_add_f32_dpp v161, v161, v161 row_half_mirror row_mask:0xf bank_mask:0xf bound_ctrl:1
	v_pk_fma_f32 v[72:73], v[32:33], v[172:173], v[218:219] op_sel_hi:[1,0,1]
	v_pk_fma_f32 v[80:81], v[32:33], v[174:175], v[226:227] op_sel_hi:[1,0,1]
	v_pk_fma_f32 v[74:75], v[34:35], v[172:173], v[220:221] op_sel_hi:[1,0,1]
	v_pk_fma_f32 v[82:83], v[34:35], v[174:175], v[228:229] op_sel_hi:[1,0,1]
	v_pk_fma_f32 v[76:77], v[36:37], v[172:173], v[222:223] op_sel_hi:[1,0,1]
	v_pk_fma_f32 v[84:85], v[36:37], v[174:175], v[230:231] op_sel_hi:[1,0,1]
	v_pk_fma_f32 v[78:79], v[38:39], v[172:173], v[224:225] op_sel_hi:[1,0,1]
	v_pk_fma_f32 v[86:87], v[38:39], v[174:175], v[234:235] op_sel_hi:[1,0,1]
	s_mov_b32 exec_lo, 0x01010101
	s_mov_b32 exec_hi, 0x01010101
	ds_write_b64 v1, v[160:161] offset:54016
	s_mov_b64 exec, -1
	s_waitcnt lgkmcnt(1)
	v_pk_mul_f32 v[164:165], v[72:73], v[176:177]
	v_pk_mul_f32 v[166:167], v[80:81], v[176:177]
	ds_read_b128 v[208:211], v2 offset:16896
	v_pk_mul_f32 v[168:169], v[72:73], v[48:49]
	v_pk_mul_f32 v[170:171], v[80:81], v[48:49]
	ds_read_b128 v[212:215], v2 offset:16912
	v_pk_fma_f32 v[164:165], v[74:75], v[178:179], v[164:165]
	v_pk_fma_f32 v[166:167], v[82:83], v[178:179], v[166:167]
	ds_read_b128 v[4:7], v2 offset:4864
	v_pk_fma_f32 v[168:169], v[74:75], v[50:51], v[168:169]
	v_pk_fma_f32 v[170:171], v[82:83], v[50:51], v[170:171]
	ds_read_b128 v[8:11], v2 offset:4880
	v_pk_fma_f32 v[164:165], v[76:77], v[180:181], v[164:165]
	v_pk_fma_f32 v[166:167], v[84:85], v[180:181], v[166:167]
	ds_read_b128 v[40:43], v2 offset:13056
	v_pk_fma_f32 v[168:169], v[76:77], v[52:53], v[168:169]
	v_pk_fma_f32 v[170:171], v[84:85], v[52:53], v[170:171]
	ds_read_b128 v[44:47], v2 offset:13072
	v_pk_fma_f32 v[164:165], v[78:79], v[182:183], v[164:165]
	v_pk_fma_f32 v[166:167], v[86:87], v[182:183], v[166:167]
	ds_read_b64 v[26:27], v3 offset:41728
	v_pk_fma_f32 v[168:169], v[78:79], v[54:55], v[168:169]
	v_pk_fma_f32 v[170:171], v[86:87], v[54:55], v[170:171]
	ds_read_b128 v[12:15], v2 offset:768
	v_pk_mul_f32 v[218:219], v[216:217], v[200:201] op_sel_hi:[0,1]
	v_pk_mul_f32 v[226:227], v[216:217], v[200:201] op_sel:[1,0]
	ds_read_b128 v[28:31], v2 offset:784
	v_pk_mul_f32 v[220:221], v[216:217], v[202:203] op_sel_hi:[0,1]
	v_pk_mul_f32 v[228:229], v[216:217], v[202:203] op_sel:[1,0]
	ds_read_b128 v[32:35], v2 offset:8960
	v_pk_mul_f32 v[222:223], v[216:217], v[204:205] op_sel_hi:[0,1]
	v_pk_mul_f32 v[230:231], v[216:217], v[204:205] op_sel:[1,0]
	ds_read_b128 v[36:39], v2 offset:8976
	v_pk_mul_f32 v[224:225], v[216:217], v[206:207] op_sel_hi:[0,1]
	v_pk_mul_f32 v[234:235], v[216:217], v[206:207] op_sel:[1,0]
	v_add_f32_e32 v172, v164, v165
	v_add_f32_e32 v174, v166, v167
	v_add_f32_e32 v160, v168, v169
	v_add_f32_e32 v161, v170, v171
	v_pk_fma_f32 v[218:219], v[72:73], v[184:185], v[218:219]
	v_pk_fma_f32 v[226:227], v[80:81], v[184:185], v[226:227]
	v_pk_fma_f32 v[220:221], v[74:75], v[186:187], v[220:221]
	v_pk_fma_f32 v[228:229], v[82:83], v[186:187], v[228:229]
	v_add_f32_dpp v172, v172, v172 quad_perm:[1,0,3,2] row_mask:0xf bank_mask:0xf bound_ctrl:1
	v_add_f32_dpp v174, v174, v174 quad_perm:[1,0,3,2] row_mask:0xf bank_mask:0xf bound_ctrl:1
	v_add_f32_dpp v160, v160, v160 quad_perm:[1,0,3,2] row_mask:0xf bank_mask:0xf bound_ctrl:1
	v_add_f32_dpp v161, v161, v161 quad_perm:[1,0,3,2] row_mask:0xf bank_mask:0xf bound_ctrl:1
	v_pk_fma_f32 v[222:223], v[76:77], v[188:189], v[222:223]
	v_pk_fma_f32 v[230:231], v[84:85], v[188:189], v[230:231]
	v_pk_fma_f32 v[224:225], v[78:79], v[190:191], v[224:225]
	v_pk_fma_f32 v[234:235], v[86:87], v[190:191], v[234:235]
	v_add_f32_dpp v172, v172, v172 quad_perm:[2,3,0,1] row_mask:0xf bank_mask:0xf bound_ctrl:1
	v_add_f32_dpp v174, v174, v174 quad_perm:[2,3,0,1] row_mask:0xf bank_mask:0xf bound_ctrl:1
	v_add_f32_dpp v160, v160, v160 quad_perm:[2,3,0,1] row_mask:0xf bank_mask:0xf bound_ctrl:1
	v_add_f32_dpp v161, v161, v161 quad_perm:[2,3,0,1] row_mask:0xf bank_mask:0xf bound_ctrl:1
	v_add_f32_dpp v172, v172, v172 row_half_mirror row_mask:0xf bank_mask:0xf bound_ctrl:1
	v_add_f32_dpp v174, v174, v174 row_half_mirror row_mask:0xf bank_mask:0xf bound_ctrl:1
	v_add_f32_dpp v160, v160, v160 row_half_mirror row_mask:0xf bank_mask:0xf bound_ctrl:1
	v_add_f32_dpp v161, v161, v161 row_half_mirror row_mask:0xf bank_mask:0xf bound_ctrl:1
	v_pk_fma_f32 v[72:73], v[192:193], v[172:173], v[218:219] op_sel_hi:[1,0,1]
	v_pk_fma_f32 v[80:81], v[192:193], v[174:175], v[226:227] op_sel_hi:[1,0,1]
	v_pk_fma_f32 v[74:75], v[194:195], v[172:173], v[220:221] op_sel_hi:[1,0,1]
	v_pk_fma_f32 v[82:83], v[194:195], v[174:175], v[228:229] op_sel_hi:[1,0,1]
	v_pk_fma_f32 v[76:77], v[196:197], v[172:173], v[222:223] op_sel_hi:[1,0,1]
	v_pk_fma_f32 v[84:85], v[196:197], v[174:175], v[230:231] op_sel_hi:[1,0,1]
	v_pk_fma_f32 v[78:79], v[198:199], v[172:173], v[224:225] op_sel_hi:[1,0,1]
	v_pk_fma_f32 v[86:87], v[198:199], v[174:175], v[234:235] op_sel_hi:[1,0,1]
	s_mov_b32 exec_lo, 0x01010101
	s_mov_b32 exec_hi, 0x01010101
	ds_write_b64 v1, v[160:161] offset:54272
	s_mov_b64 exec, -1
	s_waitcnt lgkmcnt(1)
	v_pk_mul_f32 v[164:165], v[72:73], v[4:5]
	v_pk_mul_f32 v[166:167], v[80:81], v[4:5]
	ds_read_b128 v[48:51], v2 offset:17152
	v_pk_mul_f32 v[168:169], v[72:73], v[208:209]
	v_pk_mul_f32 v[170:171], v[80:81], v[208:209]
	ds_read_b128 v[52:55], v2 offset:17168
	v_pk_fma_f32 v[164:165], v[74:75], v[6:7], v[164:165]
	v_pk_fma_f32 v[166:167], v[82:83], v[6:7], v[166:167]
	ds_read_b128 v[176:179], v2 offset:5120
	v_pk_fma_f32 v[168:169], v[74:75], v[210:211], v[168:169]
	v_pk_fma_f32 v[170:171], v[82:83], v[210:211], v[170:171]
	ds_read_b128 v[180:183], v2 offset:5136
	v_pk_fma_f32 v[164:165], v[76:77], v[8:9], v[164:165]
	v_pk_fma_f32 v[166:167], v[84:85], v[8:9], v[166:167]
	ds_read_b128 v[200:203], v2 offset:13312
	v_pk_fma_f32 v[168:169], v[76:77], v[212:213], v[168:169]
	v_pk_fma_f32 v[170:171], v[84:85], v[212:213], v[170:171]
	ds_read_b128 v[204:207], v2 offset:13328
	v_pk_fma_f32 v[164:165], v[78:79], v[10:11], v[164:165]
	v_pk_fma_f32 v[166:167], v[86:87], v[10:11], v[166:167]
	ds_read_b64 v[216:217], v3 offset:41984
	v_pk_fma_f32 v[168:169], v[78:79], v[214:215], v[168:169]
	v_pk_fma_f32 v[170:171], v[86:87], v[214:215], v[170:171]
	ds_read_b128 v[184:187], v2 offset:1024
	v_pk_mul_f32 v[218:219], v[26:27], v[40:41] op_sel_hi:[0,1]
	v_pk_mul_f32 v[226:227], v[26:27], v[40:41] op_sel:[1,0]
	ds_read_b128 v[188:191], v2 offset:1040
	v_pk_mul_f32 v[220:221], v[26:27], v[42:43] op_sel_hi:[0,1]
	v_pk_mul_f32 v[228:229], v[26:27], v[42:43] op_sel:[1,0]
	ds_read_b128 v[192:195], v2 offset:9216
	v_pk_mul_f32 v[222:223], v[26:27], v[44:45] op_sel_hi:[0,1]
	v_pk_mul_f32 v[230:231], v[26:27], v[44:45] op_sel:[1,0]
	ds_read_b128 v[196:199], v2 offset:9232
	v_pk_mul_f32 v[224:225], v[26:27], v[46:47] op_sel_hi:[0,1]
	v_pk_mul_f32 v[234:235], v[26:27], v[46:47] op_sel:[1,0]
	v_add_f32_e32 v172, v164, v165
	v_add_f32_e32 v174, v166, v167
	v_add_f32_e32 v160, v168, v169
	v_add_f32_e32 v161, v170, v171
	v_pk_fma_f32 v[218:219], v[72:73], v[12:13], v[218:219]
	v_pk_fma_f32 v[226:227], v[80:81], v[12:13], v[226:227]
	v_pk_fma_f32 v[220:221], v[74:75], v[14:15], v[220:221]
	v_pk_fma_f32 v[228:229], v[82:83], v[14:15], v[228:229]
	v_add_f32_dpp v172, v172, v172 quad_perm:[1,0,3,2] row_mask:0xf bank_mask:0xf bound_ctrl:1
	v_add_f32_dpp v174, v174, v174 quad_perm:[1,0,3,2] row_mask:0xf bank_mask:0xf bound_ctrl:1
	v_add_f32_dpp v160, v160, v160 quad_perm:[1,0,3,2] row_mask:0xf bank_mask:0xf bound_ctrl:1
	v_add_f32_dpp v161, v161, v161 quad_perm:[1,0,3,2] row_mask:0xf bank_mask:0xf bound_ctrl:1
	v_pk_fma_f32 v[222:223], v[76:77], v[28:29], v[222:223]
	v_pk_fma_f32 v[230:231], v[84:85], v[28:29], v[230:231]
	v_pk_fma_f32 v[224:225], v[78:79], v[30:31], v[224:225]
	v_pk_fma_f32 v[234:235], v[86:87], v[30:31], v[234:235]
	v_add_f32_dpp v172, v172, v172 quad_perm:[2,3,0,1] row_mask:0xf bank_mask:0xf bound_ctrl:1
	v_add_f32_dpp v174, v174, v174 quad_perm:[2,3,0,1] row_mask:0xf bank_mask:0xf bound_ctrl:1
	v_add_f32_dpp v160, v160, v160 quad_perm:[2,3,0,1] row_mask:0xf bank_mask:0xf bound_ctrl:1
	v_add_f32_dpp v161, v161, v161 quad_perm:[2,3,0,1] row_mask:0xf bank_mask:0xf bound_ctrl:1
	v_add_f32_dpp v172, v172, v172 row_half_mirror row_mask:0xf bank_mask:0xf bound_ctrl:1
	v_add_f32_dpp v174, v174, v174 row_half_mirror row_mask:0xf bank_mask:0xf bound_ctrl:1
	v_add_f32_dpp v160, v160, v160 row_half_mirror row_mask:0xf bank_mask:0xf bound_ctrl:1
	v_add_f32_dpp v161, v161, v161 row_half_mirror row_mask:0xf bank_mask:0xf bound_ctrl:1
	v_pk_fma_f32 v[72:73], v[32:33], v[172:173], v[218:219] op_sel_hi:[1,0,1]
	v_pk_fma_f32 v[80:81], v[32:33], v[174:175], v[226:227] op_sel_hi:[1,0,1]
	v_pk_fma_f32 v[74:75], v[34:35], v[172:173], v[220:221] op_sel_hi:[1,0,1]
	v_pk_fma_f32 v[82:83], v[34:35], v[174:175], v[228:229] op_sel_hi:[1,0,1]
	v_pk_fma_f32 v[76:77], v[36:37], v[172:173], v[222:223] op_sel_hi:[1,0,1]
	v_pk_fma_f32 v[84:85], v[36:37], v[174:175], v[230:231] op_sel_hi:[1,0,1]
	v_pk_fma_f32 v[78:79], v[38:39], v[172:173], v[224:225] op_sel_hi:[1,0,1]
	v_pk_fma_f32 v[86:87], v[38:39], v[174:175], v[234:235] op_sel_hi:[1,0,1]
	s_mov_b32 exec_lo, 0x01010101
	s_mov_b32 exec_hi, 0x01010101
	ds_write_b64 v1, v[160:161] offset:54528
	s_mov_b64 exec, -1
	s_waitcnt lgkmcnt(1)
	v_pk_mul_f32 v[164:165], v[72:73], v[176:177]
	v_pk_mul_f32 v[166:167], v[80:81], v[176:177]
	ds_read_b128 v[208:211], v2 offset:17408
	v_pk_mul_f32 v[168:169], v[72:73], v[48:49]
	v_pk_mul_f32 v[170:171], v[80:81], v[48:49]
	ds_read_b128 v[212:215], v2 offset:17424
	v_pk_fma_f32 v[164:165], v[74:75], v[178:179], v[164:165]
	v_pk_fma_f32 v[166:167], v[82:83], v[178:179], v[166:167]
	ds_read_b128 v[4:7], v2 offset:5376
	v_pk_fma_f32 v[168:169], v[74:75], v[50:51], v[168:169]
	v_pk_fma_f32 v[170:171], v[82:83], v[50:51], v[170:171]
	ds_read_b128 v[8:11], v2 offset:5392
	v_pk_fma_f32 v[164:165], v[76:77], v[180:181], v[164:165]
	v_pk_fma_f32 v[166:167], v[84:85], v[180:181], v[166:167]
	ds_read_b128 v[40:43], v2 offset:13568
	v_pk_fma_f32 v[168:169], v[76:77], v[52:53], v[168:169]
	v_pk_fma_f32 v[170:171], v[84:85], v[52:53], v[170:171]
	ds_read_b128 v[44:47], v2 offset:13584
	v_pk_fma_f32 v[164:165], v[78:79], v[182:183], v[164:165]
	v_pk_fma_f32 v[166:167], v[86:87], v[182:183], v[166:167]
	ds_read_b64 v[26:27], v3 offset:42240
	v_pk_fma_f32 v[168:169], v[78:79], v[54:55], v[168:169]
	v_pk_fma_f32 v[170:171], v[86:87], v[54:55], v[170:171]
	ds_read_b128 v[12:15], v2 offset:1280
	v_pk_mul_f32 v[218:219], v[216:217], v[200:201] op_sel_hi:[0,1]
	v_pk_mul_f32 v[226:227], v[216:217], v[200:201] op_sel:[1,0]
	ds_read_b128 v[28:31], v2 offset:1296
	v_pk_mul_f32 v[220:221], v[216:217], v[202:203] op_sel_hi:[0,1]
	v_pk_mul_f32 v[228:229], v[216:217], v[202:203] op_sel:[1,0]
	ds_read_b128 v[32:35], v2 offset:9472
	v_pk_mul_f32 v[222:223], v[216:217], v[204:205] op_sel_hi:[0,1]
	v_pk_mul_f32 v[230:231], v[216:217], v[204:205] op_sel:[1,0]
	ds_read_b128 v[36:39], v2 offset:9488
	v_pk_mul_f32 v[224:225], v[216:217], v[206:207] op_sel_hi:[0,1]
	v_pk_mul_f32 v[234:235], v[216:217], v[206:207] op_sel:[1,0]
	v_add_f32_e32 v172, v164, v165
	v_add_f32_e32 v174, v166, v167
	v_add_f32_e32 v160, v168, v169
	v_add_f32_e32 v161, v170, v171
	v_pk_fma_f32 v[218:219], v[72:73], v[184:185], v[218:219]
	v_pk_fma_f32 v[226:227], v[80:81], v[184:185], v[226:227]
	v_pk_fma_f32 v[220:221], v[74:75], v[186:187], v[220:221]
	v_pk_fma_f32 v[228:229], v[82:83], v[186:187], v[228:229]
	v_add_f32_dpp v172, v172, v172 quad_perm:[1,0,3,2] row_mask:0xf bank_mask:0xf bound_ctrl:1
	v_add_f32_dpp v174, v174, v174 quad_perm:[1,0,3,2] row_mask:0xf bank_mask:0xf bound_ctrl:1
	v_add_f32_dpp v160, v160, v160 quad_perm:[1,0,3,2] row_mask:0xf bank_mask:0xf bound_ctrl:1
	v_add_f32_dpp v161, v161, v161 quad_perm:[1,0,3,2] row_mask:0xf bank_mask:0xf bound_ctrl:1
	v_pk_fma_f32 v[222:223], v[76:77], v[188:189], v[222:223]
	v_pk_fma_f32 v[230:231], v[84:85], v[188:189], v[230:231]
	v_pk_fma_f32 v[224:225], v[78:79], v[190:191], v[224:225]
	v_pk_fma_f32 v[234:235], v[86:87], v[190:191], v[234:235]
	v_add_f32_dpp v172, v172, v172 quad_perm:[2,3,0,1] row_mask:0xf bank_mask:0xf bound_ctrl:1
	v_add_f32_dpp v174, v174, v174 quad_perm:[2,3,0,1] row_mask:0xf bank_mask:0xf bound_ctrl:1
	v_add_f32_dpp v160, v160, v160 quad_perm:[2,3,0,1] row_mask:0xf bank_mask:0xf bound_ctrl:1
	v_add_f32_dpp v161, v161, v161 quad_perm:[2,3,0,1] row_mask:0xf bank_mask:0xf bound_ctrl:1
	v_add_f32_dpp v172, v172, v172 row_half_mirror row_mask:0xf bank_mask:0xf bound_ctrl:1
	v_add_f32_dpp v174, v174, v174 row_half_mirror row_mask:0xf bank_mask:0xf bound_ctrl:1
	v_add_f32_dpp v160, v160, v160 row_half_mirror row_mask:0xf bank_mask:0xf bound_ctrl:1
	v_add_f32_dpp v161, v161, v161 row_half_mirror row_mask:0xf bank_mask:0xf bound_ctrl:1
	v_pk_fma_f32 v[72:73], v[192:193], v[172:173], v[218:219] op_sel_hi:[1,0,1]
	v_pk_fma_f32 v[80:81], v[192:193], v[174:175], v[226:227] op_sel_hi:[1,0,1]
	v_pk_fma_f32 v[74:75], v[194:195], v[172:173], v[220:221] op_sel_hi:[1,0,1]
	v_pk_fma_f32 v[82:83], v[194:195], v[174:175], v[228:229] op_sel_hi:[1,0,1]
	v_pk_fma_f32 v[76:77], v[196:197], v[172:173], v[222:223] op_sel_hi:[1,0,1]
	v_pk_fma_f32 v[84:85], v[196:197], v[174:175], v[230:231] op_sel_hi:[1,0,1]
	v_pk_fma_f32 v[78:79], v[198:199], v[172:173], v[224:225] op_sel_hi:[1,0,1]
	v_pk_fma_f32 v[86:87], v[198:199], v[174:175], v[234:235] op_sel_hi:[1,0,1]
	s_mov_b32 exec_lo, 0x01010101
	s_mov_b32 exec_hi, 0x01010101
	ds_write_b64 v1, v[160:161] offset:54784
	s_mov_b64 exec, -1
	s_waitcnt lgkmcnt(1)
	v_pk_mul_f32 v[164:165], v[72:73], v[4:5]
	v_pk_mul_f32 v[166:167], v[80:81], v[4:5]
	ds_read_b128 v[48:51], v2 offset:17664
	v_pk_mul_f32 v[168:169], v[72:73], v[208:209]
	v_pk_mul_f32 v[170:171], v[80:81], v[208:209]
	ds_read_b128 v[52:55], v2 offset:17680
	v_pk_fma_f32 v[164:165], v[74:75], v[6:7], v[164:165]
	v_pk_fma_f32 v[166:167], v[82:83], v[6:7], v[166:167]
	ds_read_b128 v[176:179], v2 offset:5632
	v_pk_fma_f32 v[168:169], v[74:75], v[210:211], v[168:169]
	v_pk_fma_f32 v[170:171], v[82:83], v[210:211], v[170:171]
	ds_read_b128 v[180:183], v2 offset:5648
	v_pk_fma_f32 v[164:165], v[76:77], v[8:9], v[164:165]
	v_pk_fma_f32 v[166:167], v[84:85], v[8:9], v[166:167]
	ds_read_b128 v[200:203], v2 offset:13824
	v_pk_fma_f32 v[168:169], v[76:77], v[212:213], v[168:169]
	v_pk_fma_f32 v[170:171], v[84:85], v[212:213], v[170:171]
	ds_read_b128 v[204:207], v2 offset:13840
	v_pk_fma_f32 v[164:165], v[78:79], v[10:11], v[164:165]
	v_pk_fma_f32 v[166:167], v[86:87], v[10:11], v[166:167]
	ds_read_b64 v[216:217], v3 offset:42496
	v_pk_fma_f32 v[168:169], v[78:79], v[214:215], v[168:169]
	v_pk_fma_f32 v[170:171], v[86:87], v[214:215], v[170:171]
	ds_read_b128 v[184:187], v2 offset:1536
	v_pk_mul_f32 v[218:219], v[26:27], v[40:41] op_sel_hi:[0,1]
	v_pk_mul_f32 v[226:227], v[26:27], v[40:41] op_sel:[1,0]
	ds_read_b128 v[188:191], v2 offset:1552
	v_pk_mul_f32 v[220:221], v[26:27], v[42:43] op_sel_hi:[0,1]
	v_pk_mul_f32 v[228:229], v[26:27], v[42:43] op_sel:[1,0]
	ds_read_b128 v[192:195], v2 offset:9728
	v_pk_mul_f32 v[222:223], v[26:27], v[44:45] op_sel_hi:[0,1]
	v_pk_mul_f32 v[230:231], v[26:27], v[44:45] op_sel:[1,0]
	ds_read_b128 v[196:199], v2 offset:9744
	v_pk_mul_f32 v[224:225], v[26:27], v[46:47] op_sel_hi:[0,1]
	v_pk_mul_f32 v[234:235], v[26:27], v[46:47] op_sel:[1,0]
	v_add_f32_e32 v172, v164, v165
	v_add_f32_e32 v174, v166, v167
	v_add_f32_e32 v160, v168, v169
	v_add_f32_e32 v161, v170, v171
	v_pk_fma_f32 v[218:219], v[72:73], v[12:13], v[218:219]
	v_pk_fma_f32 v[226:227], v[80:81], v[12:13], v[226:227]
	v_pk_fma_f32 v[220:221], v[74:75], v[14:15], v[220:221]
	v_pk_fma_f32 v[228:229], v[82:83], v[14:15], v[228:229]
	v_add_f32_dpp v172, v172, v172 quad_perm:[1,0,3,2] row_mask:0xf bank_mask:0xf bound_ctrl:1
	v_add_f32_dpp v174, v174, v174 quad_perm:[1,0,3,2] row_mask:0xf bank_mask:0xf bound_ctrl:1
	v_add_f32_dpp v160, v160, v160 quad_perm:[1,0,3,2] row_mask:0xf bank_mask:0xf bound_ctrl:1
	v_add_f32_dpp v161, v161, v161 quad_perm:[1,0,3,2] row_mask:0xf bank_mask:0xf bound_ctrl:1
	v_pk_fma_f32 v[222:223], v[76:77], v[28:29], v[222:223]
	v_pk_fma_f32 v[230:231], v[84:85], v[28:29], v[230:231]
	v_pk_fma_f32 v[224:225], v[78:79], v[30:31], v[224:225]
	v_pk_fma_f32 v[234:235], v[86:87], v[30:31], v[234:235]
	v_add_f32_dpp v172, v172, v172 quad_perm:[2,3,0,1] row_mask:0xf bank_mask:0xf bound_ctrl:1
	v_add_f32_dpp v174, v174, v174 quad_perm:[2,3,0,1] row_mask:0xf bank_mask:0xf bound_ctrl:1
	v_add_f32_dpp v160, v160, v160 quad_perm:[2,3,0,1] row_mask:0xf bank_mask:0xf bound_ctrl:1
	v_add_f32_dpp v161, v161, v161 quad_perm:[2,3,0,1] row_mask:0xf bank_mask:0xf bound_ctrl:1
	v_add_f32_dpp v172, v172, v172 row_half_mirror row_mask:0xf bank_mask:0xf bound_ctrl:1
	v_add_f32_dpp v174, v174, v174 row_half_mirror row_mask:0xf bank_mask:0xf bound_ctrl:1
	v_add_f32_dpp v160, v160, v160 row_half_mirror row_mask:0xf bank_mask:0xf bound_ctrl:1
	v_add_f32_dpp v161, v161, v161 row_half_mirror row_mask:0xf bank_mask:0xf bound_ctrl:1
	v_pk_fma_f32 v[72:73], v[32:33], v[172:173], v[218:219] op_sel_hi:[1,0,1]
	v_pk_fma_f32 v[80:81], v[32:33], v[174:175], v[226:227] op_sel_hi:[1,0,1]
	v_pk_fma_f32 v[74:75], v[34:35], v[172:173], v[220:221] op_sel_hi:[1,0,1]
	v_pk_fma_f32 v[82:83], v[34:35], v[174:175], v[228:229] op_sel_hi:[1,0,1]
	v_pk_fma_f32 v[76:77], v[36:37], v[172:173], v[222:223] op_sel_hi:[1,0,1]
	v_pk_fma_f32 v[84:85], v[36:37], v[174:175], v[230:231] op_sel_hi:[1,0,1]
	v_pk_fma_f32 v[78:79], v[38:39], v[172:173], v[224:225] op_sel_hi:[1,0,1]
	v_pk_fma_f32 v[86:87], v[38:39], v[174:175], v[234:235] op_sel_hi:[1,0,1]
	s_mov_b32 exec_lo, 0x01010101
	s_mov_b32 exec_hi, 0x01010101
	ds_write_b64 v1, v[160:161] offset:55040
	s_mov_b64 exec, -1
	s_waitcnt lgkmcnt(1)
	v_pk_mul_f32 v[164:165], v[72:73], v[176:177]
	v_pk_mul_f32 v[166:167], v[80:81], v[176:177]
	ds_read_b128 v[208:211], v2 offset:17920
	v_pk_mul_f32 v[168:169], v[72:73], v[48:49]
	v_pk_mul_f32 v[170:171], v[80:81], v[48:49]
	ds_read_b128 v[212:215], v2 offset:17936
	v_pk_fma_f32 v[164:165], v[74:75], v[178:179], v[164:165]
	v_pk_fma_f32 v[166:167], v[82:83], v[178:179], v[166:167]
	ds_read_b128 v[4:7], v2 offset:5888
	v_pk_fma_f32 v[168:169], v[74:75], v[50:51], v[168:169]
	v_pk_fma_f32 v[170:171], v[82:83], v[50:51], v[170:171]
	ds_read_b128 v[8:11], v2 offset:5904
	v_pk_fma_f32 v[164:165], v[76:77], v[180:181], v[164:165]
	v_pk_fma_f32 v[166:167], v[84:85], v[180:181], v[166:167]
	ds_read_b128 v[40:43], v2 offset:14080
	v_pk_fma_f32 v[168:169], v[76:77], v[52:53], v[168:169]
	v_pk_fma_f32 v[170:171], v[84:85], v[52:53], v[170:171]
	ds_read_b128 v[44:47], v2 offset:14096
	v_pk_fma_f32 v[164:165], v[78:79], v[182:183], v[164:165]
	v_pk_fma_f32 v[166:167], v[86:87], v[182:183], v[166:167]
	ds_read_b64 v[26:27], v3 offset:42752
	v_pk_fma_f32 v[168:169], v[78:79], v[54:55], v[168:169]
	v_pk_fma_f32 v[170:171], v[86:87], v[54:55], v[170:171]
	ds_read_b128 v[12:15], v2 offset:1792
	v_pk_mul_f32 v[218:219], v[216:217], v[200:201] op_sel_hi:[0,1]
	v_pk_mul_f32 v[226:227], v[216:217], v[200:201] op_sel:[1,0]
	ds_read_b128 v[28:31], v2 offset:1808
	v_pk_mul_f32 v[220:221], v[216:217], v[202:203] op_sel_hi:[0,1]
	v_pk_mul_f32 v[228:229], v[216:217], v[202:203] op_sel:[1,0]
	ds_read_b128 v[32:35], v2 offset:9984
	v_pk_mul_f32 v[222:223], v[216:217], v[204:205] op_sel_hi:[0,1]
	v_pk_mul_f32 v[230:231], v[216:217], v[204:205] op_sel:[1,0]
	ds_read_b128 v[36:39], v2 offset:10000
	v_pk_mul_f32 v[224:225], v[216:217], v[206:207] op_sel_hi:[0,1]
	v_pk_mul_f32 v[234:235], v[216:217], v[206:207] op_sel:[1,0]
	v_add_f32_e32 v172, v164, v165
	v_add_f32_e32 v174, v166, v167
	v_add_f32_e32 v160, v168, v169
	v_add_f32_e32 v161, v170, v171
	v_pk_fma_f32 v[218:219], v[72:73], v[184:185], v[218:219]
	v_pk_fma_f32 v[226:227], v[80:81], v[184:185], v[226:227]
	v_pk_fma_f32 v[220:221], v[74:75], v[186:187], v[220:221]
	v_pk_fma_f32 v[228:229], v[82:83], v[186:187], v[228:229]
	v_add_f32_dpp v172, v172, v172 quad_perm:[1,0,3,2] row_mask:0xf bank_mask:0xf bound_ctrl:1
	v_add_f32_dpp v174, v174, v174 quad_perm:[1,0,3,2] row_mask:0xf bank_mask:0xf bound_ctrl:1
	v_add_f32_dpp v160, v160, v160 quad_perm:[1,0,3,2] row_mask:0xf bank_mask:0xf bound_ctrl:1
	v_add_f32_dpp v161, v161, v161 quad_perm:[1,0,3,2] row_mask:0xf bank_mask:0xf bound_ctrl:1
	v_pk_fma_f32 v[222:223], v[76:77], v[188:189], v[222:223]
	v_pk_fma_f32 v[230:231], v[84:85], v[188:189], v[230:231]
	v_pk_fma_f32 v[224:225], v[78:79], v[190:191], v[224:225]
	v_pk_fma_f32 v[234:235], v[86:87], v[190:191], v[234:235]
	v_add_f32_dpp v172, v172, v172 quad_perm:[2,3,0,1] row_mask:0xf bank_mask:0xf bound_ctrl:1
	v_add_f32_dpp v174, v174, v174 quad_perm:[2,3,0,1] row_mask:0xf bank_mask:0xf bound_ctrl:1
	v_add_f32_dpp v160, v160, v160 quad_perm:[2,3,0,1] row_mask:0xf bank_mask:0xf bound_ctrl:1
	v_add_f32_dpp v161, v161, v161 quad_perm:[2,3,0,1] row_mask:0xf bank_mask:0xf bound_ctrl:1
	v_add_f32_dpp v172, v172, v172 row_half_mirror row_mask:0xf bank_mask:0xf bound_ctrl:1
	v_add_f32_dpp v174, v174, v174 row_half_mirror row_mask:0xf bank_mask:0xf bound_ctrl:1
	v_add_f32_dpp v160, v160, v160 row_half_mirror row_mask:0xf bank_mask:0xf bound_ctrl:1
	v_add_f32_dpp v161, v161, v161 row_half_mirror row_mask:0xf bank_mask:0xf bound_ctrl:1
	v_pk_fma_f32 v[72:73], v[192:193], v[172:173], v[218:219] op_sel_hi:[1,0,1]
	v_pk_fma_f32 v[80:81], v[192:193], v[174:175], v[226:227] op_sel_hi:[1,0,1]
	v_pk_fma_f32 v[74:75], v[194:195], v[172:173], v[220:221] op_sel_hi:[1,0,1]
	v_pk_fma_f32 v[82:83], v[194:195], v[174:175], v[228:229] op_sel_hi:[1,0,1]
	v_pk_fma_f32 v[76:77], v[196:197], v[172:173], v[222:223] op_sel_hi:[1,0,1]
	v_pk_fma_f32 v[84:85], v[196:197], v[174:175], v[230:231] op_sel_hi:[1,0,1]
	v_pk_fma_f32 v[78:79], v[198:199], v[172:173], v[224:225] op_sel_hi:[1,0,1]
	v_pk_fma_f32 v[86:87], v[198:199], v[174:175], v[234:235] op_sel_hi:[1,0,1]
	s_mov_b32 exec_lo, 0x01010101
	s_mov_b32 exec_hi, 0x01010101
	ds_write_b64 v1, v[160:161] offset:55296
	s_mov_b64 exec, -1
	s_waitcnt lgkmcnt(1)
	v_pk_mul_f32 v[164:165], v[72:73], v[4:5]
	v_pk_mul_f32 v[166:167], v[80:81], v[4:5]
	ds_read_b128 v[48:51], v2 offset:18176
	v_pk_mul_f32 v[168:169], v[72:73], v[208:209]
	v_pk_mul_f32 v[170:171], v[80:81], v[208:209]
	ds_read_b128 v[52:55], v2 offset:18192
	v_pk_fma_f32 v[164:165], v[74:75], v[6:7], v[164:165]
	v_pk_fma_f32 v[166:167], v[82:83], v[6:7], v[166:167]
	ds_read_b128 v[176:179], v2 offset:6144
	v_pk_fma_f32 v[168:169], v[74:75], v[210:211], v[168:169]
	v_pk_fma_f32 v[170:171], v[82:83], v[210:211], v[170:171]
	ds_read_b128 v[180:183], v2 offset:6160
	v_pk_fma_f32 v[164:165], v[76:77], v[8:9], v[164:165]
	v_pk_fma_f32 v[166:167], v[84:85], v[8:9], v[166:167]
	ds_read_b128 v[200:203], v2 offset:14336
	v_pk_fma_f32 v[168:169], v[76:77], v[212:213], v[168:169]
	v_pk_fma_f32 v[170:171], v[84:85], v[212:213], v[170:171]
	ds_read_b128 v[204:207], v2 offset:14352
	v_pk_fma_f32 v[164:165], v[78:79], v[10:11], v[164:165]
	v_pk_fma_f32 v[166:167], v[86:87], v[10:11], v[166:167]
	ds_read_b64 v[216:217], v3 offset:43008
	v_pk_fma_f32 v[168:169], v[78:79], v[214:215], v[168:169]
	v_pk_fma_f32 v[170:171], v[86:87], v[214:215], v[170:171]
	ds_read_b128 v[184:187], v2 offset:2048
	v_pk_mul_f32 v[218:219], v[26:27], v[40:41] op_sel_hi:[0,1]
	v_pk_mul_f32 v[226:227], v[26:27], v[40:41] op_sel:[1,0]
	ds_read_b128 v[188:191], v2 offset:2064
	v_pk_mul_f32 v[220:221], v[26:27], v[42:43] op_sel_hi:[0,1]
	v_pk_mul_f32 v[228:229], v[26:27], v[42:43] op_sel:[1,0]
	ds_read_b128 v[192:195], v2 offset:10240
	v_pk_mul_f32 v[222:223], v[26:27], v[44:45] op_sel_hi:[0,1]
	v_pk_mul_f32 v[230:231], v[26:27], v[44:45] op_sel:[1,0]
	ds_read_b128 v[196:199], v2 offset:10256
	v_pk_mul_f32 v[224:225], v[26:27], v[46:47] op_sel_hi:[0,1]
	v_pk_mul_f32 v[234:235], v[26:27], v[46:47] op_sel:[1,0]
	v_add_f32_e32 v172, v164, v165
	v_add_f32_e32 v174, v166, v167
	v_add_f32_e32 v160, v168, v169
	v_add_f32_e32 v161, v170, v171
	v_pk_fma_f32 v[218:219], v[72:73], v[12:13], v[218:219]
	v_pk_fma_f32 v[226:227], v[80:81], v[12:13], v[226:227]
	v_pk_fma_f32 v[220:221], v[74:75], v[14:15], v[220:221]
	v_pk_fma_f32 v[228:229], v[82:83], v[14:15], v[228:229]
	v_add_f32_dpp v172, v172, v172 quad_perm:[1,0,3,2] row_mask:0xf bank_mask:0xf bound_ctrl:1
	v_add_f32_dpp v174, v174, v174 quad_perm:[1,0,3,2] row_mask:0xf bank_mask:0xf bound_ctrl:1
	v_add_f32_dpp v160, v160, v160 quad_perm:[1,0,3,2] row_mask:0xf bank_mask:0xf bound_ctrl:1
	v_add_f32_dpp v161, v161, v161 quad_perm:[1,0,3,2] row_mask:0xf bank_mask:0xf bound_ctrl:1
	v_pk_fma_f32 v[222:223], v[76:77], v[28:29], v[222:223]
	v_pk_fma_f32 v[230:231], v[84:85], v[28:29], v[230:231]
	v_pk_fma_f32 v[224:225], v[78:79], v[30:31], v[224:225]
	v_pk_fma_f32 v[234:235], v[86:87], v[30:31], v[234:235]
	v_add_f32_dpp v172, v172, v172 quad_perm:[2,3,0,1] row_mask:0xf bank_mask:0xf bound_ctrl:1
	v_add_f32_dpp v174, v174, v174 quad_perm:[2,3,0,1] row_mask:0xf bank_mask:0xf bound_ctrl:1
	v_add_f32_dpp v160, v160, v160 quad_perm:[2,3,0,1] row_mask:0xf bank_mask:0xf bound_ctrl:1
	v_add_f32_dpp v161, v161, v161 quad_perm:[2,3,0,1] row_mask:0xf bank_mask:0xf bound_ctrl:1
	v_add_f32_dpp v172, v172, v172 row_half_mirror row_mask:0xf bank_mask:0xf bound_ctrl:1
	v_add_f32_dpp v174, v174, v174 row_half_mirror row_mask:0xf bank_mask:0xf bound_ctrl:1
	v_add_f32_dpp v160, v160, v160 row_half_mirror row_mask:0xf bank_mask:0xf bound_ctrl:1
	v_add_f32_dpp v161, v161, v161 row_half_mirror row_mask:0xf bank_mask:0xf bound_ctrl:1
	v_pk_fma_f32 v[72:73], v[32:33], v[172:173], v[218:219] op_sel_hi:[1,0,1]
	v_pk_fma_f32 v[80:81], v[32:33], v[174:175], v[226:227] op_sel_hi:[1,0,1]
	v_pk_fma_f32 v[74:75], v[34:35], v[172:173], v[220:221] op_sel_hi:[1,0,1]
	v_pk_fma_f32 v[82:83], v[34:35], v[174:175], v[228:229] op_sel_hi:[1,0,1]
	v_pk_fma_f32 v[76:77], v[36:37], v[172:173], v[222:223] op_sel_hi:[1,0,1]
	v_pk_fma_f32 v[84:85], v[36:37], v[174:175], v[230:231] op_sel_hi:[1,0,1]
	v_pk_fma_f32 v[78:79], v[38:39], v[172:173], v[224:225] op_sel_hi:[1,0,1]
	v_pk_fma_f32 v[86:87], v[38:39], v[174:175], v[234:235] op_sel_hi:[1,0,1]
	s_mov_b32 exec_lo, 0x01010101
	s_mov_b32 exec_hi, 0x01010101
	ds_write_b64 v1, v[160:161] offset:55552
	s_mov_b64 exec, -1
	s_waitcnt lgkmcnt(1)
	v_pk_mul_f32 v[164:165], v[72:73], v[176:177]
	v_pk_mul_f32 v[166:167], v[80:81], v[176:177]
	ds_read_b128 v[208:211], v2 offset:18432
	v_pk_mul_f32 v[168:169], v[72:73], v[48:49]
	v_pk_mul_f32 v[170:171], v[80:81], v[48:49]
	ds_read_b128 v[212:215], v2 offset:18448
	v_pk_fma_f32 v[164:165], v[74:75], v[178:179], v[164:165]
	v_pk_fma_f32 v[166:167], v[82:83], v[178:179], v[166:167]
	ds_read_b128 v[4:7], v2 offset:6400
	v_pk_fma_f32 v[168:169], v[74:75], v[50:51], v[168:169]
	v_pk_fma_f32 v[170:171], v[82:83], v[50:51], v[170:171]
	ds_read_b128 v[8:11], v2 offset:6416
	v_pk_fma_f32 v[164:165], v[76:77], v[180:181], v[164:165]
	v_pk_fma_f32 v[166:167], v[84:85], v[180:181], v[166:167]
	ds_read_b128 v[40:43], v2 offset:14592
	v_pk_fma_f32 v[168:169], v[76:77], v[52:53], v[168:169]
	v_pk_fma_f32 v[170:171], v[84:85], v[52:53], v[170:171]
	ds_read_b128 v[44:47], v2 offset:14608
	v_pk_fma_f32 v[164:165], v[78:79], v[182:183], v[164:165]
	v_pk_fma_f32 v[166:167], v[86:87], v[182:183], v[166:167]
	ds_read_b64 v[26:27], v3 offset:43264
	v_pk_fma_f32 v[168:169], v[78:79], v[54:55], v[168:169]
	v_pk_fma_f32 v[170:171], v[86:87], v[54:55], v[170:171]
	ds_read_b128 v[12:15], v2 offset:2304
	v_pk_mul_f32 v[218:219], v[216:217], v[200:201] op_sel_hi:[0,1]
	v_pk_mul_f32 v[226:227], v[216:217], v[200:201] op_sel:[1,0]
	ds_read_b128 v[28:31], v2 offset:2320
	v_pk_mul_f32 v[220:221], v[216:217], v[202:203] op_sel_hi:[0,1]
	v_pk_mul_f32 v[228:229], v[216:217], v[202:203] op_sel:[1,0]
	ds_read_b128 v[32:35], v2 offset:10496
	v_pk_mul_f32 v[222:223], v[216:217], v[204:205] op_sel_hi:[0,1]
	v_pk_mul_f32 v[230:231], v[216:217], v[204:205] op_sel:[1,0]
	ds_read_b128 v[36:39], v2 offset:10512
	v_pk_mul_f32 v[224:225], v[216:217], v[206:207] op_sel_hi:[0,1]
	v_pk_mul_f32 v[234:235], v[216:217], v[206:207] op_sel:[1,0]
	v_add_f32_e32 v172, v164, v165
	v_add_f32_e32 v174, v166, v167
	v_add_f32_e32 v160, v168, v169
	v_add_f32_e32 v161, v170, v171
	v_pk_fma_f32 v[218:219], v[72:73], v[184:185], v[218:219]
	v_pk_fma_f32 v[226:227], v[80:81], v[184:185], v[226:227]
	v_pk_fma_f32 v[220:221], v[74:75], v[186:187], v[220:221]
	v_pk_fma_f32 v[228:229], v[82:83], v[186:187], v[228:229]
	v_add_f32_dpp v172, v172, v172 quad_perm:[1,0,3,2] row_mask:0xf bank_mask:0xf bound_ctrl:1
	v_add_f32_dpp v174, v174, v174 quad_perm:[1,0,3,2] row_mask:0xf bank_mask:0xf bound_ctrl:1
	v_add_f32_dpp v160, v160, v160 quad_perm:[1,0,3,2] row_mask:0xf bank_mask:0xf bound_ctrl:1
	v_add_f32_dpp v161, v161, v161 quad_perm:[1,0,3,2] row_mask:0xf bank_mask:0xf bound_ctrl:1
	v_pk_fma_f32 v[222:223], v[76:77], v[188:189], v[222:223]
	v_pk_fma_f32 v[230:231], v[84:85], v[188:189], v[230:231]
	v_pk_fma_f32 v[224:225], v[78:79], v[190:191], v[224:225]
	v_pk_fma_f32 v[234:235], v[86:87], v[190:191], v[234:235]
	v_add_f32_dpp v172, v172, v172 quad_perm:[2,3,0,1] row_mask:0xf bank_mask:0xf bound_ctrl:1
	v_add_f32_dpp v174, v174, v174 quad_perm:[2,3,0,1] row_mask:0xf bank_mask:0xf bound_ctrl:1
	v_add_f32_dpp v160, v160, v160 quad_perm:[2,3,0,1] row_mask:0xf bank_mask:0xf bound_ctrl:1
	v_add_f32_dpp v161, v161, v161 quad_perm:[2,3,0,1] row_mask:0xf bank_mask:0xf bound_ctrl:1
	v_add_f32_dpp v172, v172, v172 row_half_mirror row_mask:0xf bank_mask:0xf bound_ctrl:1
	v_add_f32_dpp v174, v174, v174 row_half_mirror row_mask:0xf bank_mask:0xf bound_ctrl:1
	v_add_f32_dpp v160, v160, v160 row_half_mirror row_mask:0xf bank_mask:0xf bound_ctrl:1
	v_add_f32_dpp v161, v161, v161 row_half_mirror row_mask:0xf bank_mask:0xf bound_ctrl:1
	v_pk_fma_f32 v[72:73], v[192:193], v[172:173], v[218:219] op_sel_hi:[1,0,1]
	v_pk_fma_f32 v[80:81], v[192:193], v[174:175], v[226:227] op_sel_hi:[1,0,1]
	v_pk_fma_f32 v[74:75], v[194:195], v[172:173], v[220:221] op_sel_hi:[1,0,1]
	v_pk_fma_f32 v[82:83], v[194:195], v[174:175], v[228:229] op_sel_hi:[1,0,1]
	v_pk_fma_f32 v[76:77], v[196:197], v[172:173], v[222:223] op_sel_hi:[1,0,1]
	v_pk_fma_f32 v[84:85], v[196:197], v[174:175], v[230:231] op_sel_hi:[1,0,1]
	v_pk_fma_f32 v[78:79], v[198:199], v[172:173], v[224:225] op_sel_hi:[1,0,1]
	v_pk_fma_f32 v[86:87], v[198:199], v[174:175], v[234:235] op_sel_hi:[1,0,1]
	s_mov_b32 exec_lo, 0x01010101
	s_mov_b32 exec_hi, 0x01010101
	ds_write_b64 v1, v[160:161] offset:55808
	s_mov_b64 exec, -1
	s_waitcnt lgkmcnt(1)
	v_pk_mul_f32 v[164:165], v[72:73], v[4:5]
	v_pk_mul_f32 v[166:167], v[80:81], v[4:5]
	ds_read_b128 v[48:51], v2 offset:18688
	v_pk_mul_f32 v[168:169], v[72:73], v[208:209]
	v_pk_mul_f32 v[170:171], v[80:81], v[208:209]
	ds_read_b128 v[52:55], v2 offset:18704
	v_pk_fma_f32 v[164:165], v[74:75], v[6:7], v[164:165]
	v_pk_fma_f32 v[166:167], v[82:83], v[6:7], v[166:167]
	ds_read_b128 v[176:179], v2 offset:6656
	v_pk_fma_f32 v[168:169], v[74:75], v[210:211], v[168:169]
	v_pk_fma_f32 v[170:171], v[82:83], v[210:211], v[170:171]
	ds_read_b128 v[180:183], v2 offset:6672
	v_pk_fma_f32 v[164:165], v[76:77], v[8:9], v[164:165]
	v_pk_fma_f32 v[166:167], v[84:85], v[8:9], v[166:167]
	ds_read_b128 v[200:203], v2 offset:14848
	v_pk_fma_f32 v[168:169], v[76:77], v[212:213], v[168:169]
	v_pk_fma_f32 v[170:171], v[84:85], v[212:213], v[170:171]
	ds_read_b128 v[204:207], v2 offset:14864
	v_pk_fma_f32 v[164:165], v[78:79], v[10:11], v[164:165]
	v_pk_fma_f32 v[166:167], v[86:87], v[10:11], v[166:167]
	ds_read_b64 v[216:217], v3 offset:43520
	v_pk_fma_f32 v[168:169], v[78:79], v[214:215], v[168:169]
	v_pk_fma_f32 v[170:171], v[86:87], v[214:215], v[170:171]
	ds_read_b128 v[184:187], v2 offset:2560
	v_pk_mul_f32 v[218:219], v[26:27], v[40:41] op_sel_hi:[0,1]
	v_pk_mul_f32 v[226:227], v[26:27], v[40:41] op_sel:[1,0]
	ds_read_b128 v[188:191], v2 offset:2576
	v_pk_mul_f32 v[220:221], v[26:27], v[42:43] op_sel_hi:[0,1]
	v_pk_mul_f32 v[228:229], v[26:27], v[42:43] op_sel:[1,0]
	ds_read_b128 v[192:195], v2 offset:10752
	v_pk_mul_f32 v[222:223], v[26:27], v[44:45] op_sel_hi:[0,1]
	v_pk_mul_f32 v[230:231], v[26:27], v[44:45] op_sel:[1,0]
	ds_read_b128 v[196:199], v2 offset:10768
	v_pk_mul_f32 v[224:225], v[26:27], v[46:47] op_sel_hi:[0,1]
	v_pk_mul_f32 v[234:235], v[26:27], v[46:47] op_sel:[1,0]
	v_add_f32_e32 v172, v164, v165
	v_add_f32_e32 v174, v166, v167
	v_add_f32_e32 v160, v168, v169
	v_add_f32_e32 v161, v170, v171
	v_pk_fma_f32 v[218:219], v[72:73], v[12:13], v[218:219]
	v_pk_fma_f32 v[226:227], v[80:81], v[12:13], v[226:227]
	v_pk_fma_f32 v[220:221], v[74:75], v[14:15], v[220:221]
	v_pk_fma_f32 v[228:229], v[82:83], v[14:15], v[228:229]
	v_add_f32_dpp v172, v172, v172 quad_perm:[1,0,3,2] row_mask:0xf bank_mask:0xf bound_ctrl:1
	v_add_f32_dpp v174, v174, v174 quad_perm:[1,0,3,2] row_mask:0xf bank_mask:0xf bound_ctrl:1
	v_add_f32_dpp v160, v160, v160 quad_perm:[1,0,3,2] row_mask:0xf bank_mask:0xf bound_ctrl:1
	v_add_f32_dpp v161, v161, v161 quad_perm:[1,0,3,2] row_mask:0xf bank_mask:0xf bound_ctrl:1
	v_pk_fma_f32 v[222:223], v[76:77], v[28:29], v[222:223]
	v_pk_fma_f32 v[230:231], v[84:85], v[28:29], v[230:231]
	v_pk_fma_f32 v[224:225], v[78:79], v[30:31], v[224:225]
	v_pk_fma_f32 v[234:235], v[86:87], v[30:31], v[234:235]
	v_add_f32_dpp v172, v172, v172 quad_perm:[2,3,0,1] row_mask:0xf bank_mask:0xf bound_ctrl:1
	v_add_f32_dpp v174, v174, v174 quad_perm:[2,3,0,1] row_mask:0xf bank_mask:0xf bound_ctrl:1
	v_add_f32_dpp v160, v160, v160 quad_perm:[2,3,0,1] row_mask:0xf bank_mask:0xf bound_ctrl:1
	v_add_f32_dpp v161, v161, v161 quad_perm:[2,3,0,1] row_mask:0xf bank_mask:0xf bound_ctrl:1
	v_add_f32_dpp v172, v172, v172 row_half_mirror row_mask:0xf bank_mask:0xf bound_ctrl:1
	v_add_f32_dpp v174, v174, v174 row_half_mirror row_mask:0xf bank_mask:0xf bound_ctrl:1
	v_add_f32_dpp v160, v160, v160 row_half_mirror row_mask:0xf bank_mask:0xf bound_ctrl:1
	v_add_f32_dpp v161, v161, v161 row_half_mirror row_mask:0xf bank_mask:0xf bound_ctrl:1
	v_pk_fma_f32 v[72:73], v[32:33], v[172:173], v[218:219] op_sel_hi:[1,0,1]
	v_pk_fma_f32 v[80:81], v[32:33], v[174:175], v[226:227] op_sel_hi:[1,0,1]
	v_pk_fma_f32 v[74:75], v[34:35], v[172:173], v[220:221] op_sel_hi:[1,0,1]
	v_pk_fma_f32 v[82:83], v[34:35], v[174:175], v[228:229] op_sel_hi:[1,0,1]
	v_pk_fma_f32 v[76:77], v[36:37], v[172:173], v[222:223] op_sel_hi:[1,0,1]
	v_pk_fma_f32 v[84:85], v[36:37], v[174:175], v[230:231] op_sel_hi:[1,0,1]
	v_pk_fma_f32 v[78:79], v[38:39], v[172:173], v[224:225] op_sel_hi:[1,0,1]
	v_pk_fma_f32 v[86:87], v[38:39], v[174:175], v[234:235] op_sel_hi:[1,0,1]
	s_mov_b32 exec_lo, 0x01010101
	s_mov_b32 exec_hi, 0x01010101
	ds_write_b64 v1, v[160:161] offset:56064
	s_mov_b64 exec, -1
	s_waitcnt lgkmcnt(1)
	v_pk_mul_f32 v[164:165], v[72:73], v[176:177]
	v_pk_mul_f32 v[166:167], v[80:81], v[176:177]
	ds_read_b128 v[208:211], v2 offset:18944
	v_pk_mul_f32 v[168:169], v[72:73], v[48:49]
	v_pk_mul_f32 v[170:171], v[80:81], v[48:49]
	ds_read_b128 v[212:215], v2 offset:18960
	v_pk_fma_f32 v[164:165], v[74:75], v[178:179], v[164:165]
	v_pk_fma_f32 v[166:167], v[82:83], v[178:179], v[166:167]
	ds_read_b128 v[4:7], v2 offset:6912
	v_pk_fma_f32 v[168:169], v[74:75], v[50:51], v[168:169]
	v_pk_fma_f32 v[170:171], v[82:83], v[50:51], v[170:171]
	ds_read_b128 v[8:11], v2 offset:6928
	v_pk_fma_f32 v[164:165], v[76:77], v[180:181], v[164:165]
	v_pk_fma_f32 v[166:167], v[84:85], v[180:181], v[166:167]
	ds_read_b128 v[40:43], v2 offset:15104
	v_pk_fma_f32 v[168:169], v[76:77], v[52:53], v[168:169]
	v_pk_fma_f32 v[170:171], v[84:85], v[52:53], v[170:171]
	ds_read_b128 v[44:47], v2 offset:15120
	v_pk_fma_f32 v[164:165], v[78:79], v[182:183], v[164:165]
	v_pk_fma_f32 v[166:167], v[86:87], v[182:183], v[166:167]
	ds_read_b64 v[26:27], v3 offset:43776
	v_pk_fma_f32 v[168:169], v[78:79], v[54:55], v[168:169]
	v_pk_fma_f32 v[170:171], v[86:87], v[54:55], v[170:171]
	ds_read_b128 v[12:15], v2 offset:2816
	v_pk_mul_f32 v[218:219], v[216:217], v[200:201] op_sel_hi:[0,1]
	v_pk_mul_f32 v[226:227], v[216:217], v[200:201] op_sel:[1,0]
	ds_read_b128 v[28:31], v2 offset:2832
	v_pk_mul_f32 v[220:221], v[216:217], v[202:203] op_sel_hi:[0,1]
	v_pk_mul_f32 v[228:229], v[216:217], v[202:203] op_sel:[1,0]
	ds_read_b128 v[32:35], v2 offset:11008
	v_pk_mul_f32 v[222:223], v[216:217], v[204:205] op_sel_hi:[0,1]
	v_pk_mul_f32 v[230:231], v[216:217], v[204:205] op_sel:[1,0]
	ds_read_b128 v[36:39], v2 offset:11024
	v_pk_mul_f32 v[224:225], v[216:217], v[206:207] op_sel_hi:[0,1]
	v_pk_mul_f32 v[234:235], v[216:217], v[206:207] op_sel:[1,0]
	v_add_f32_e32 v172, v164, v165
	v_add_f32_e32 v174, v166, v167
	v_add_f32_e32 v160, v168, v169
	v_add_f32_e32 v161, v170, v171
	v_pk_fma_f32 v[218:219], v[72:73], v[184:185], v[218:219]
	v_pk_fma_f32 v[226:227], v[80:81], v[184:185], v[226:227]
	v_pk_fma_f32 v[220:221], v[74:75], v[186:187], v[220:221]
	v_pk_fma_f32 v[228:229], v[82:83], v[186:187], v[228:229]
	v_add_f32_dpp v172, v172, v172 quad_perm:[1,0,3,2] row_mask:0xf bank_mask:0xf bound_ctrl:1
	v_add_f32_dpp v174, v174, v174 quad_perm:[1,0,3,2] row_mask:0xf bank_mask:0xf bound_ctrl:1
	v_add_f32_dpp v160, v160, v160 quad_perm:[1,0,3,2] row_mask:0xf bank_mask:0xf bound_ctrl:1
	v_add_f32_dpp v161, v161, v161 quad_perm:[1,0,3,2] row_mask:0xf bank_mask:0xf bound_ctrl:1
	v_pk_fma_f32 v[222:223], v[76:77], v[188:189], v[222:223]
	v_pk_fma_f32 v[230:231], v[84:85], v[188:189], v[230:231]
	v_pk_fma_f32 v[224:225], v[78:79], v[190:191], v[224:225]
	v_pk_fma_f32 v[234:235], v[86:87], v[190:191], v[234:235]
	v_add_f32_dpp v172, v172, v172 quad_perm:[2,3,0,1] row_mask:0xf bank_mask:0xf bound_ctrl:1
	v_add_f32_dpp v174, v174, v174 quad_perm:[2,3,0,1] row_mask:0xf bank_mask:0xf bound_ctrl:1
	v_add_f32_dpp v160, v160, v160 quad_perm:[2,3,0,1] row_mask:0xf bank_mask:0xf bound_ctrl:1
	v_add_f32_dpp v161, v161, v161 quad_perm:[2,3,0,1] row_mask:0xf bank_mask:0xf bound_ctrl:1
	v_add_f32_dpp v172, v172, v172 row_half_mirror row_mask:0xf bank_mask:0xf bound_ctrl:1
	v_add_f32_dpp v174, v174, v174 row_half_mirror row_mask:0xf bank_mask:0xf bound_ctrl:1
	v_add_f32_dpp v160, v160, v160 row_half_mirror row_mask:0xf bank_mask:0xf bound_ctrl:1
	v_add_f32_dpp v161, v161, v161 row_half_mirror row_mask:0xf bank_mask:0xf bound_ctrl:1
	v_pk_fma_f32 v[72:73], v[192:193], v[172:173], v[218:219] op_sel_hi:[1,0,1]
	v_pk_fma_f32 v[80:81], v[192:193], v[174:175], v[226:227] op_sel_hi:[1,0,1]
	v_pk_fma_f32 v[74:75], v[194:195], v[172:173], v[220:221] op_sel_hi:[1,0,1]
	v_pk_fma_f32 v[82:83], v[194:195], v[174:175], v[228:229] op_sel_hi:[1,0,1]
	v_pk_fma_f32 v[76:77], v[196:197], v[172:173], v[222:223] op_sel_hi:[1,0,1]
	v_pk_fma_f32 v[84:85], v[196:197], v[174:175], v[230:231] op_sel_hi:[1,0,1]
	v_pk_fma_f32 v[78:79], v[198:199], v[172:173], v[224:225] op_sel_hi:[1,0,1]
	v_pk_fma_f32 v[86:87], v[198:199], v[174:175], v[234:235] op_sel_hi:[1,0,1]
	s_mov_b32 exec_lo, 0x01010101
	s_mov_b32 exec_hi, 0x01010101
	ds_write_b64 v1, v[160:161] offset:56320
	s_mov_b64 exec, -1
	s_waitcnt lgkmcnt(1)
	v_pk_mul_f32 v[164:165], v[72:73], v[4:5]
	v_pk_mul_f32 v[166:167], v[80:81], v[4:5]
	ds_read_b128 v[48:51], v2 offset:19200
	v_pk_mul_f32 v[168:169], v[72:73], v[208:209]
	v_pk_mul_f32 v[170:171], v[80:81], v[208:209]
	ds_read_b128 v[52:55], v2 offset:19216
	v_pk_fma_f32 v[164:165], v[74:75], v[6:7], v[164:165]
	v_pk_fma_f32 v[166:167], v[82:83], v[6:7], v[166:167]
	ds_read_b128 v[176:179], v2 offset:7168
	v_pk_fma_f32 v[168:169], v[74:75], v[210:211], v[168:169]
	v_pk_fma_f32 v[170:171], v[82:83], v[210:211], v[170:171]
	ds_read_b128 v[180:183], v2 offset:7184
	v_pk_fma_f32 v[164:165], v[76:77], v[8:9], v[164:165]
	v_pk_fma_f32 v[166:167], v[84:85], v[8:9], v[166:167]
	ds_read_b128 v[200:203], v2 offset:15360
	v_pk_fma_f32 v[168:169], v[76:77], v[212:213], v[168:169]
	v_pk_fma_f32 v[170:171], v[84:85], v[212:213], v[170:171]
	ds_read_b128 v[204:207], v2 offset:15376
	v_pk_fma_f32 v[164:165], v[78:79], v[10:11], v[164:165]
	v_pk_fma_f32 v[166:167], v[86:87], v[10:11], v[166:167]
	ds_read_b64 v[216:217], v3 offset:44032
	v_pk_fma_f32 v[168:169], v[78:79], v[214:215], v[168:169]
	v_pk_fma_f32 v[170:171], v[86:87], v[214:215], v[170:171]
	ds_read_b128 v[184:187], v2 offset:3072
	v_pk_mul_f32 v[218:219], v[26:27], v[40:41] op_sel_hi:[0,1]
	v_pk_mul_f32 v[226:227], v[26:27], v[40:41] op_sel:[1,0]
	ds_read_b128 v[188:191], v2 offset:3088
	v_pk_mul_f32 v[220:221], v[26:27], v[42:43] op_sel_hi:[0,1]
	v_pk_mul_f32 v[228:229], v[26:27], v[42:43] op_sel:[1,0]
	ds_read_b128 v[192:195], v2 offset:11264
	v_pk_mul_f32 v[222:223], v[26:27], v[44:45] op_sel_hi:[0,1]
	v_pk_mul_f32 v[230:231], v[26:27], v[44:45] op_sel:[1,0]
	ds_read_b128 v[196:199], v2 offset:11280
	v_pk_mul_f32 v[224:225], v[26:27], v[46:47] op_sel_hi:[0,1]
	v_pk_mul_f32 v[234:235], v[26:27], v[46:47] op_sel:[1,0]
	v_add_f32_e32 v172, v164, v165
	v_add_f32_e32 v174, v166, v167
	v_add_f32_e32 v160, v168, v169
	v_add_f32_e32 v161, v170, v171
	v_pk_fma_f32 v[218:219], v[72:73], v[12:13], v[218:219]
	v_pk_fma_f32 v[226:227], v[80:81], v[12:13], v[226:227]
	v_pk_fma_f32 v[220:221], v[74:75], v[14:15], v[220:221]
	v_pk_fma_f32 v[228:229], v[82:83], v[14:15], v[228:229]
	v_add_f32_dpp v172, v172, v172 quad_perm:[1,0,3,2] row_mask:0xf bank_mask:0xf bound_ctrl:1
	v_add_f32_dpp v174, v174, v174 quad_perm:[1,0,3,2] row_mask:0xf bank_mask:0xf bound_ctrl:1
	v_add_f32_dpp v160, v160, v160 quad_perm:[1,0,3,2] row_mask:0xf bank_mask:0xf bound_ctrl:1
	v_add_f32_dpp v161, v161, v161 quad_perm:[1,0,3,2] row_mask:0xf bank_mask:0xf bound_ctrl:1
	v_pk_fma_f32 v[222:223], v[76:77], v[28:29], v[222:223]
	v_pk_fma_f32 v[230:231], v[84:85], v[28:29], v[230:231]
	v_pk_fma_f32 v[224:225], v[78:79], v[30:31], v[224:225]
	v_pk_fma_f32 v[234:235], v[86:87], v[30:31], v[234:235]
	v_add_f32_dpp v172, v172, v172 quad_perm:[2,3,0,1] row_mask:0xf bank_mask:0xf bound_ctrl:1
	v_add_f32_dpp v174, v174, v174 quad_perm:[2,3,0,1] row_mask:0xf bank_mask:0xf bound_ctrl:1
	v_add_f32_dpp v160, v160, v160 quad_perm:[2,3,0,1] row_mask:0xf bank_mask:0xf bound_ctrl:1
	v_add_f32_dpp v161, v161, v161 quad_perm:[2,3,0,1] row_mask:0xf bank_mask:0xf bound_ctrl:1
	v_add_f32_dpp v172, v172, v172 row_half_mirror row_mask:0xf bank_mask:0xf bound_ctrl:1
	v_add_f32_dpp v174, v174, v174 row_half_mirror row_mask:0xf bank_mask:0xf bound_ctrl:1
	v_add_f32_dpp v160, v160, v160 row_half_mirror row_mask:0xf bank_mask:0xf bound_ctrl:1
	v_add_f32_dpp v161, v161, v161 row_half_mirror row_mask:0xf bank_mask:0xf bound_ctrl:1
	v_pk_fma_f32 v[72:73], v[32:33], v[172:173], v[218:219] op_sel_hi:[1,0,1]
	v_pk_fma_f32 v[80:81], v[32:33], v[174:175], v[226:227] op_sel_hi:[1,0,1]
	v_pk_fma_f32 v[74:75], v[34:35], v[172:173], v[220:221] op_sel_hi:[1,0,1]
	v_pk_fma_f32 v[82:83], v[34:35], v[174:175], v[228:229] op_sel_hi:[1,0,1]
	v_pk_fma_f32 v[76:77], v[36:37], v[172:173], v[222:223] op_sel_hi:[1,0,1]
	v_pk_fma_f32 v[84:85], v[36:37], v[174:175], v[230:231] op_sel_hi:[1,0,1]
	v_pk_fma_f32 v[78:79], v[38:39], v[172:173], v[224:225] op_sel_hi:[1,0,1]
	v_pk_fma_f32 v[86:87], v[38:39], v[174:175], v[234:235] op_sel_hi:[1,0,1]
	s_mov_b32 exec_lo, 0x01010101
	s_mov_b32 exec_hi, 0x01010101
	ds_write_b64 v1, v[160:161] offset:56576
	s_mov_b64 exec, -1
	s_waitcnt lgkmcnt(1)
	v_pk_mul_f32 v[164:165], v[72:73], v[176:177]
	v_pk_mul_f32 v[166:167], v[80:81], v[176:177]
	ds_read_b128 v[208:211], v2 offset:19456
	v_pk_mul_f32 v[168:169], v[72:73], v[48:49]
	v_pk_mul_f32 v[170:171], v[80:81], v[48:49]
	ds_read_b128 v[212:215], v2 offset:19472
	v_pk_fma_f32 v[164:165], v[74:75], v[178:179], v[164:165]
	v_pk_fma_f32 v[166:167], v[82:83], v[178:179], v[166:167]
	ds_read_b128 v[4:7], v2 offset:7424
	v_pk_fma_f32 v[168:169], v[74:75], v[50:51], v[168:169]
	v_pk_fma_f32 v[170:171], v[82:83], v[50:51], v[170:171]
	ds_read_b128 v[8:11], v2 offset:7440
	v_pk_fma_f32 v[164:165], v[76:77], v[180:181], v[164:165]
	v_pk_fma_f32 v[166:167], v[84:85], v[180:181], v[166:167]
	ds_read_b128 v[40:43], v2 offset:15616
	v_pk_fma_f32 v[168:169], v[76:77], v[52:53], v[168:169]
	v_pk_fma_f32 v[170:171], v[84:85], v[52:53], v[170:171]
	ds_read_b128 v[44:47], v2 offset:15632
	v_pk_fma_f32 v[164:165], v[78:79], v[182:183], v[164:165]
	v_pk_fma_f32 v[166:167], v[86:87], v[182:183], v[166:167]
	ds_read_b64 v[26:27], v3 offset:44288
	v_pk_fma_f32 v[168:169], v[78:79], v[54:55], v[168:169]
	v_pk_fma_f32 v[170:171], v[86:87], v[54:55], v[170:171]
	ds_read_b128 v[12:15], v2 offset:3328
	v_pk_mul_f32 v[218:219], v[216:217], v[200:201] op_sel_hi:[0,1]
	v_pk_mul_f32 v[226:227], v[216:217], v[200:201] op_sel:[1,0]
	ds_read_b128 v[28:31], v2 offset:3344
	v_pk_mul_f32 v[220:221], v[216:217], v[202:203] op_sel_hi:[0,1]
	v_pk_mul_f32 v[228:229], v[216:217], v[202:203] op_sel:[1,0]
	ds_read_b128 v[32:35], v2 offset:11520
	v_pk_mul_f32 v[222:223], v[216:217], v[204:205] op_sel_hi:[0,1]
	v_pk_mul_f32 v[230:231], v[216:217], v[204:205] op_sel:[1,0]
	ds_read_b128 v[36:39], v2 offset:11536
	v_pk_mul_f32 v[224:225], v[216:217], v[206:207] op_sel_hi:[0,1]
	v_pk_mul_f32 v[234:235], v[216:217], v[206:207] op_sel:[1,0]
	v_add_f32_e32 v172, v164, v165
	v_add_f32_e32 v174, v166, v167
	v_add_f32_e32 v160, v168, v169
	v_add_f32_e32 v161, v170, v171
	v_pk_fma_f32 v[218:219], v[72:73], v[184:185], v[218:219]
	v_pk_fma_f32 v[226:227], v[80:81], v[184:185], v[226:227]
	v_pk_fma_f32 v[220:221], v[74:75], v[186:187], v[220:221]
	v_pk_fma_f32 v[228:229], v[82:83], v[186:187], v[228:229]
	v_add_f32_dpp v172, v172, v172 quad_perm:[1,0,3,2] row_mask:0xf bank_mask:0xf bound_ctrl:1
	v_add_f32_dpp v174, v174, v174 quad_perm:[1,0,3,2] row_mask:0xf bank_mask:0xf bound_ctrl:1
	v_add_f32_dpp v160, v160, v160 quad_perm:[1,0,3,2] row_mask:0xf bank_mask:0xf bound_ctrl:1
	v_add_f32_dpp v161, v161, v161 quad_perm:[1,0,3,2] row_mask:0xf bank_mask:0xf bound_ctrl:1
	v_pk_fma_f32 v[222:223], v[76:77], v[188:189], v[222:223]
	v_pk_fma_f32 v[230:231], v[84:85], v[188:189], v[230:231]
	v_pk_fma_f32 v[224:225], v[78:79], v[190:191], v[224:225]
	v_pk_fma_f32 v[234:235], v[86:87], v[190:191], v[234:235]
	v_add_f32_dpp v172, v172, v172 quad_perm:[2,3,0,1] row_mask:0xf bank_mask:0xf bound_ctrl:1
	v_add_f32_dpp v174, v174, v174 quad_perm:[2,3,0,1] row_mask:0xf bank_mask:0xf bound_ctrl:1
	v_add_f32_dpp v160, v160, v160 quad_perm:[2,3,0,1] row_mask:0xf bank_mask:0xf bound_ctrl:1
	v_add_f32_dpp v161, v161, v161 quad_perm:[2,3,0,1] row_mask:0xf bank_mask:0xf bound_ctrl:1
	v_add_f32_dpp v172, v172, v172 row_half_mirror row_mask:0xf bank_mask:0xf bound_ctrl:1
	v_add_f32_dpp v174, v174, v174 row_half_mirror row_mask:0xf bank_mask:0xf bound_ctrl:1
	v_add_f32_dpp v160, v160, v160 row_half_mirror row_mask:0xf bank_mask:0xf bound_ctrl:1
	v_add_f32_dpp v161, v161, v161 row_half_mirror row_mask:0xf bank_mask:0xf bound_ctrl:1
	v_pk_fma_f32 v[72:73], v[192:193], v[172:173], v[218:219] op_sel_hi:[1,0,1]
	v_pk_fma_f32 v[80:81], v[192:193], v[174:175], v[226:227] op_sel_hi:[1,0,1]
	v_pk_fma_f32 v[74:75], v[194:195], v[172:173], v[220:221] op_sel_hi:[1,0,1]
	v_pk_fma_f32 v[82:83], v[194:195], v[174:175], v[228:229] op_sel_hi:[1,0,1]
	v_pk_fma_f32 v[76:77], v[196:197], v[172:173], v[222:223] op_sel_hi:[1,0,1]
	v_pk_fma_f32 v[84:85], v[196:197], v[174:175], v[230:231] op_sel_hi:[1,0,1]
	v_pk_fma_f32 v[78:79], v[198:199], v[172:173], v[224:225] op_sel_hi:[1,0,1]
	v_pk_fma_f32 v[86:87], v[198:199], v[174:175], v[234:235] op_sel_hi:[1,0,1]
	s_mov_b32 exec_lo, 0x01010101
	s_mov_b32 exec_hi, 0x01010101
	ds_write_b64 v1, v[160:161] offset:56832
	s_mov_b64 exec, -1
	s_waitcnt lgkmcnt(1)
	v_pk_mul_f32 v[164:165], v[72:73], v[4:5]
	v_pk_mul_f32 v[166:167], v[80:81], v[4:5]
	ds_read_b128 v[48:51], v2 offset:19712
	v_pk_mul_f32 v[168:169], v[72:73], v[208:209]
	v_pk_mul_f32 v[170:171], v[80:81], v[208:209]
	ds_read_b128 v[52:55], v2 offset:19728
	v_pk_fma_f32 v[164:165], v[74:75], v[6:7], v[164:165]
	v_pk_fma_f32 v[166:167], v[82:83], v[6:7], v[166:167]
	ds_read_b128 v[176:179], v2 offset:7680
	v_pk_fma_f32 v[168:169], v[74:75], v[210:211], v[168:169]
	v_pk_fma_f32 v[170:171], v[82:83], v[210:211], v[170:171]
	ds_read_b128 v[180:183], v2 offset:7696
	v_pk_fma_f32 v[164:165], v[76:77], v[8:9], v[164:165]
	v_pk_fma_f32 v[166:167], v[84:85], v[8:9], v[166:167]
	ds_read_b128 v[200:203], v2 offset:15872
	v_pk_fma_f32 v[168:169], v[76:77], v[212:213], v[168:169]
	v_pk_fma_f32 v[170:171], v[84:85], v[212:213], v[170:171]
	ds_read_b128 v[204:207], v2 offset:15888
	v_pk_fma_f32 v[164:165], v[78:79], v[10:11], v[164:165]
	v_pk_fma_f32 v[166:167], v[86:87], v[10:11], v[166:167]
	ds_read_b64 v[216:217], v3 offset:44544
	v_pk_fma_f32 v[168:169], v[78:79], v[214:215], v[168:169]
	v_pk_fma_f32 v[170:171], v[86:87], v[214:215], v[170:171]
	ds_read_b128 v[184:187], v2 offset:3584
	v_pk_mul_f32 v[218:219], v[26:27], v[40:41] op_sel_hi:[0,1]
	v_pk_mul_f32 v[226:227], v[26:27], v[40:41] op_sel:[1,0]
	ds_read_b128 v[188:191], v2 offset:3600
	v_pk_mul_f32 v[220:221], v[26:27], v[42:43] op_sel_hi:[0,1]
	v_pk_mul_f32 v[228:229], v[26:27], v[42:43] op_sel:[1,0]
	ds_read_b128 v[192:195], v2 offset:11776
	v_pk_mul_f32 v[222:223], v[26:27], v[44:45] op_sel_hi:[0,1]
	v_pk_mul_f32 v[230:231], v[26:27], v[44:45] op_sel:[1,0]
	ds_read_b128 v[196:199], v2 offset:11792
	v_pk_mul_f32 v[224:225], v[26:27], v[46:47] op_sel_hi:[0,1]
	v_pk_mul_f32 v[234:235], v[26:27], v[46:47] op_sel:[1,0]
	v_add_f32_e32 v172, v164, v165
	v_add_f32_e32 v174, v166, v167
	v_add_f32_e32 v160, v168, v169
	v_add_f32_e32 v161, v170, v171
	v_pk_fma_f32 v[218:219], v[72:73], v[12:13], v[218:219]
	v_pk_fma_f32 v[226:227], v[80:81], v[12:13], v[226:227]
	v_pk_fma_f32 v[220:221], v[74:75], v[14:15], v[220:221]
	v_pk_fma_f32 v[228:229], v[82:83], v[14:15], v[228:229]
	v_add_f32_dpp v172, v172, v172 quad_perm:[1,0,3,2] row_mask:0xf bank_mask:0xf bound_ctrl:1
	v_add_f32_dpp v174, v174, v174 quad_perm:[1,0,3,2] row_mask:0xf bank_mask:0xf bound_ctrl:1
	v_add_f32_dpp v160, v160, v160 quad_perm:[1,0,3,2] row_mask:0xf bank_mask:0xf bound_ctrl:1
	v_add_f32_dpp v161, v161, v161 quad_perm:[1,0,3,2] row_mask:0xf bank_mask:0xf bound_ctrl:1
	v_pk_fma_f32 v[222:223], v[76:77], v[28:29], v[222:223]
	v_pk_fma_f32 v[230:231], v[84:85], v[28:29], v[230:231]
	v_pk_fma_f32 v[224:225], v[78:79], v[30:31], v[224:225]
	v_pk_fma_f32 v[234:235], v[86:87], v[30:31], v[234:235]
	v_add_f32_dpp v172, v172, v172 quad_perm:[2,3,0,1] row_mask:0xf bank_mask:0xf bound_ctrl:1
	v_add_f32_dpp v174, v174, v174 quad_perm:[2,3,0,1] row_mask:0xf bank_mask:0xf bound_ctrl:1
	v_add_f32_dpp v160, v160, v160 quad_perm:[2,3,0,1] row_mask:0xf bank_mask:0xf bound_ctrl:1
	v_add_f32_dpp v161, v161, v161 quad_perm:[2,3,0,1] row_mask:0xf bank_mask:0xf bound_ctrl:1
	v_add_f32_dpp v172, v172, v172 row_half_mirror row_mask:0xf bank_mask:0xf bound_ctrl:1
	v_add_f32_dpp v174, v174, v174 row_half_mirror row_mask:0xf bank_mask:0xf bound_ctrl:1
	v_add_f32_dpp v160, v160, v160 row_half_mirror row_mask:0xf bank_mask:0xf bound_ctrl:1
	v_add_f32_dpp v161, v161, v161 row_half_mirror row_mask:0xf bank_mask:0xf bound_ctrl:1
	v_pk_fma_f32 v[72:73], v[32:33], v[172:173], v[218:219] op_sel_hi:[1,0,1]
	v_pk_fma_f32 v[80:81], v[32:33], v[174:175], v[226:227] op_sel_hi:[1,0,1]
	v_pk_fma_f32 v[74:75], v[34:35], v[172:173], v[220:221] op_sel_hi:[1,0,1]
	v_pk_fma_f32 v[82:83], v[34:35], v[174:175], v[228:229] op_sel_hi:[1,0,1]
	v_pk_fma_f32 v[76:77], v[36:37], v[172:173], v[222:223] op_sel_hi:[1,0,1]
	v_pk_fma_f32 v[84:85], v[36:37], v[174:175], v[230:231] op_sel_hi:[1,0,1]
	v_pk_fma_f32 v[78:79], v[38:39], v[172:173], v[224:225] op_sel_hi:[1,0,1]
	v_pk_fma_f32 v[86:87], v[38:39], v[174:175], v[234:235] op_sel_hi:[1,0,1]
	s_mov_b32 exec_lo, 0x01010101
	s_mov_b32 exec_hi, 0x01010101
	ds_write_b64 v1, v[160:161] offset:57088
	s_mov_b64 exec, -1
	s_waitcnt lgkmcnt(1)
	v_pk_mul_f32 v[164:165], v[72:73], v[176:177]
	v_pk_mul_f32 v[166:167], v[80:81], v[176:177]
	ds_read_b128 v[208:211], v2 offset:19968
	v_pk_mul_f32 v[168:169], v[72:73], v[48:49]
	v_pk_mul_f32 v[170:171], v[80:81], v[48:49]
	ds_read_b128 v[212:215], v2 offset:19984
	v_pk_fma_f32 v[164:165], v[74:75], v[178:179], v[164:165]
	v_pk_fma_f32 v[166:167], v[82:83], v[178:179], v[166:167]
	ds_read_b128 v[4:7], v2 offset:7936
	v_pk_fma_f32 v[168:169], v[74:75], v[50:51], v[168:169]
	v_pk_fma_f32 v[170:171], v[82:83], v[50:51], v[170:171]
	ds_read_b128 v[8:11], v2 offset:7952
	v_pk_fma_f32 v[164:165], v[76:77], v[180:181], v[164:165]
	v_pk_fma_f32 v[166:167], v[84:85], v[180:181], v[166:167]
	ds_read_b128 v[40:43], v2 offset:16128
	v_pk_fma_f32 v[168:169], v[76:77], v[52:53], v[168:169]
	v_pk_fma_f32 v[170:171], v[84:85], v[52:53], v[170:171]
	ds_read_b128 v[44:47], v2 offset:16144
	v_pk_fma_f32 v[164:165], v[78:79], v[182:183], v[164:165]
	v_pk_fma_f32 v[166:167], v[86:87], v[182:183], v[166:167]
	ds_read_b64 v[26:27], v3 offset:44800
	v_pk_fma_f32 v[168:169], v[78:79], v[54:55], v[168:169]
	v_pk_fma_f32 v[170:171], v[86:87], v[54:55], v[170:171]
	ds_read_b128 v[12:15], v2 offset:3840
	v_pk_mul_f32 v[218:219], v[216:217], v[200:201] op_sel_hi:[0,1]
	v_pk_mul_f32 v[226:227], v[216:217], v[200:201] op_sel:[1,0]
	ds_read_b128 v[28:31], v2 offset:3856
	v_pk_mul_f32 v[220:221], v[216:217], v[202:203] op_sel_hi:[0,1]
	v_pk_mul_f32 v[228:229], v[216:217], v[202:203] op_sel:[1,0]
	ds_read_b128 v[32:35], v2 offset:12032
	v_pk_mul_f32 v[222:223], v[216:217], v[204:205] op_sel_hi:[0,1]
	v_pk_mul_f32 v[230:231], v[216:217], v[204:205] op_sel:[1,0]
	ds_read_b128 v[36:39], v2 offset:12048
	v_pk_mul_f32 v[224:225], v[216:217], v[206:207] op_sel_hi:[0,1]
	v_pk_mul_f32 v[234:235], v[216:217], v[206:207] op_sel:[1,0]
	v_add_f32_e32 v172, v164, v165
	v_add_f32_e32 v174, v166, v167
	v_add_f32_e32 v160, v168, v169
	v_add_f32_e32 v161, v170, v171
	v_pk_fma_f32 v[218:219], v[72:73], v[184:185], v[218:219]
	v_pk_fma_f32 v[226:227], v[80:81], v[184:185], v[226:227]
	v_pk_fma_f32 v[220:221], v[74:75], v[186:187], v[220:221]
	v_pk_fma_f32 v[228:229], v[82:83], v[186:187], v[228:229]
	v_add_f32_dpp v172, v172, v172 quad_perm:[1,0,3,2] row_mask:0xf bank_mask:0xf bound_ctrl:1
	v_add_f32_dpp v174, v174, v174 quad_perm:[1,0,3,2] row_mask:0xf bank_mask:0xf bound_ctrl:1
	v_add_f32_dpp v160, v160, v160 quad_perm:[1,0,3,2] row_mask:0xf bank_mask:0xf bound_ctrl:1
	v_add_f32_dpp v161, v161, v161 quad_perm:[1,0,3,2] row_mask:0xf bank_mask:0xf bound_ctrl:1
	v_pk_fma_f32 v[222:223], v[76:77], v[188:189], v[222:223]
	v_pk_fma_f32 v[230:231], v[84:85], v[188:189], v[230:231]
	v_pk_fma_f32 v[224:225], v[78:79], v[190:191], v[224:225]
	v_pk_fma_f32 v[234:235], v[86:87], v[190:191], v[234:235]
	v_add_f32_dpp v172, v172, v172 quad_perm:[2,3,0,1] row_mask:0xf bank_mask:0xf bound_ctrl:1
	v_add_f32_dpp v174, v174, v174 quad_perm:[2,3,0,1] row_mask:0xf bank_mask:0xf bound_ctrl:1
	v_add_f32_dpp v160, v160, v160 quad_perm:[2,3,0,1] row_mask:0xf bank_mask:0xf bound_ctrl:1
	v_add_f32_dpp v161, v161, v161 quad_perm:[2,3,0,1] row_mask:0xf bank_mask:0xf bound_ctrl:1
	v_add_f32_dpp v172, v172, v172 row_half_mirror row_mask:0xf bank_mask:0xf bound_ctrl:1
	v_add_f32_dpp v174, v174, v174 row_half_mirror row_mask:0xf bank_mask:0xf bound_ctrl:1
	v_add_f32_dpp v160, v160, v160 row_half_mirror row_mask:0xf bank_mask:0xf bound_ctrl:1
	v_add_f32_dpp v161, v161, v161 row_half_mirror row_mask:0xf bank_mask:0xf bound_ctrl:1
	v_pk_fma_f32 v[72:73], v[192:193], v[172:173], v[218:219] op_sel_hi:[1,0,1]
	v_pk_fma_f32 v[80:81], v[192:193], v[174:175], v[226:227] op_sel_hi:[1,0,1]
	v_pk_fma_f32 v[74:75], v[194:195], v[172:173], v[220:221] op_sel_hi:[1,0,1]
	v_pk_fma_f32 v[82:83], v[194:195], v[174:175], v[228:229] op_sel_hi:[1,0,1]
	v_pk_fma_f32 v[76:77], v[196:197], v[172:173], v[222:223] op_sel_hi:[1,0,1]
	v_pk_fma_f32 v[84:85], v[196:197], v[174:175], v[230:231] op_sel_hi:[1,0,1]
	v_pk_fma_f32 v[78:79], v[198:199], v[172:173], v[224:225] op_sel_hi:[1,0,1]
	v_pk_fma_f32 v[86:87], v[198:199], v[174:175], v[234:235] op_sel_hi:[1,0,1]
	s_mov_b32 exec_lo, 0x01010101
	s_mov_b32 exec_hi, 0x01010101
	ds_write_b64 v1, v[160:161] offset:57344
	s_mov_b64 exec, -1
	s_waitcnt lgkmcnt(1)
	v_pk_mul_f32 v[164:165], v[72:73], v[4:5]
	v_pk_mul_f32 v[166:167], v[80:81], v[4:5]
	ds_read_b128 v[48:51], v2 offset:20224
	v_pk_mul_f32 v[168:169], v[72:73], v[208:209]
	v_pk_mul_f32 v[170:171], v[80:81], v[208:209]
	ds_read_b128 v[52:55], v2 offset:20240
	v_pk_fma_f32 v[164:165], v[74:75], v[6:7], v[164:165]
	v_pk_fma_f32 v[166:167], v[82:83], v[6:7], v[166:167]
	v_pk_fma_f32 v[168:169], v[74:75], v[210:211], v[168:169]
	v_pk_fma_f32 v[170:171], v[82:83], v[210:211], v[170:171]
	v_pk_fma_f32 v[164:165], v[76:77], v[8:9], v[164:165]
	v_pk_fma_f32 v[166:167], v[84:85], v[8:9], v[166:167]
	v_pk_fma_f32 v[168:169], v[76:77], v[212:213], v[168:169]
	v_pk_fma_f32 v[170:171], v[84:85], v[212:213], v[170:171]
	v_pk_fma_f32 v[164:165], v[78:79], v[10:11], v[164:165]
	v_pk_fma_f32 v[166:167], v[86:87], v[10:11], v[166:167]
	v_pk_fma_f32 v[168:169], v[78:79], v[214:215], v[168:169]
	v_pk_fma_f32 v[170:171], v[86:87], v[214:215], v[170:171]
	v_pk_mul_f32 v[218:219], v[26:27], v[40:41] op_sel_hi:[0,1]
	v_pk_mul_f32 v[226:227], v[26:27], v[40:41] op_sel:[1,0]
	v_pk_mul_f32 v[220:221], v[26:27], v[42:43] op_sel_hi:[0,1]
	v_pk_mul_f32 v[228:229], v[26:27], v[42:43] op_sel:[1,0]
	v_pk_mul_f32 v[222:223], v[26:27], v[44:45] op_sel_hi:[0,1]
	v_pk_mul_f32 v[230:231], v[26:27], v[44:45] op_sel:[1,0]
	v_pk_mul_f32 v[224:225], v[26:27], v[46:47] op_sel_hi:[0,1]
	v_pk_mul_f32 v[234:235], v[26:27], v[46:47] op_sel:[1,0]
	v_add_f32_e32 v172, v164, v165
	v_add_f32_e32 v174, v166, v167
	v_add_f32_e32 v160, v168, v169
	v_add_f32_e32 v161, v170, v171
	v_pk_fma_f32 v[218:219], v[72:73], v[12:13], v[218:219]
	v_pk_fma_f32 v[226:227], v[80:81], v[12:13], v[226:227]
	v_pk_fma_f32 v[220:221], v[74:75], v[14:15], v[220:221]
	v_pk_fma_f32 v[228:229], v[82:83], v[14:15], v[228:229]
	v_add_f32_dpp v172, v172, v172 quad_perm:[1,0,3,2] row_mask:0xf bank_mask:0xf bound_ctrl:1
	v_add_f32_dpp v174, v174, v174 quad_perm:[1,0,3,2] row_mask:0xf bank_mask:0xf bound_ctrl:1
	v_add_f32_dpp v160, v160, v160 quad_perm:[1,0,3,2] row_mask:0xf bank_mask:0xf bound_ctrl:1
	v_add_f32_dpp v161, v161, v161 quad_perm:[1,0,3,2] row_mask:0xf bank_mask:0xf bound_ctrl:1
	v_pk_fma_f32 v[222:223], v[76:77], v[28:29], v[222:223]
	v_pk_fma_f32 v[230:231], v[84:85], v[28:29], v[230:231]
	v_pk_fma_f32 v[224:225], v[78:79], v[30:31], v[224:225]
	v_pk_fma_f32 v[234:235], v[86:87], v[30:31], v[234:235]
	v_add_f32_dpp v172, v172, v172 quad_perm:[2,3,0,1] row_mask:0xf bank_mask:0xf bound_ctrl:1
	v_add_f32_dpp v174, v174, v174 quad_perm:[2,3,0,1] row_mask:0xf bank_mask:0xf bound_ctrl:1
	v_add_f32_dpp v160, v160, v160 quad_perm:[2,3,0,1] row_mask:0xf bank_mask:0xf bound_ctrl:1
	v_add_f32_dpp v161, v161, v161 quad_perm:[2,3,0,1] row_mask:0xf bank_mask:0xf bound_ctrl:1
	v_add_f32_dpp v172, v172, v172 row_half_mirror row_mask:0xf bank_mask:0xf bound_ctrl:1
	v_add_f32_dpp v174, v174, v174 row_half_mirror row_mask:0xf bank_mask:0xf bound_ctrl:1
	v_add_f32_dpp v160, v160, v160 row_half_mirror row_mask:0xf bank_mask:0xf bound_ctrl:1
	v_add_f32_dpp v161, v161, v161 row_half_mirror row_mask:0xf bank_mask:0xf bound_ctrl:1
	v_pk_fma_f32 v[72:73], v[32:33], v[172:173], v[218:219] op_sel_hi:[1,0,1]
	v_pk_fma_f32 v[80:81], v[32:33], v[174:175], v[226:227] op_sel_hi:[1,0,1]
	v_pk_fma_f32 v[74:75], v[34:35], v[172:173], v[220:221] op_sel_hi:[1,0,1]
	v_pk_fma_f32 v[82:83], v[34:35], v[174:175], v[228:229] op_sel_hi:[1,0,1]
	v_pk_fma_f32 v[76:77], v[36:37], v[172:173], v[222:223] op_sel_hi:[1,0,1]
	v_pk_fma_f32 v[84:85], v[36:37], v[174:175], v[230:231] op_sel_hi:[1,0,1]
	v_pk_fma_f32 v[78:79], v[38:39], v[172:173], v[224:225] op_sel_hi:[1,0,1]
	v_pk_fma_f32 v[86:87], v[38:39], v[174:175], v[234:235] op_sel_hi:[1,0,1]
	s_mov_b32 exec_lo, 0x01010101
	s_mov_b32 exec_hi, 0x01010101
	ds_write_b64 v1, v[160:161] offset:57600
	s_mov_b64 exec, -1
	s_waitcnt lgkmcnt(2)
	v_pk_mul_f32 v[168:169], v[72:73], v[48:49]
	v_pk_mul_f32 v[170:171], v[80:81], v[48:49]
	v_pk_fma_f32 v[168:169], v[74:75], v[50:51], v[168:169]
	v_pk_fma_f32 v[170:171], v[82:83], v[50:51], v[170:171]
	s_waitcnt lgkmcnt(1)
	v_pk_fma_f32 v[168:169], v[76:77], v[52:53], v[168:169]
	v_pk_fma_f32 v[170:171], v[84:85], v[52:53], v[170:171]
	v_pk_fma_f32 v[168:169], v[78:79], v[54:55], v[168:169]
	v_pk_fma_f32 v[170:171], v[86:87], v[54:55], v[170:171]
	v_add_f32_e32 v160, v168, v169
	v_add_f32_e32 v161, v170, v171
	s_nop 0
	v_add_f32_dpp v160, v160, v160 quad_perm:[1,0,3,2] row_mask:0xf bank_mask:0xf bound_ctrl:1
	v_add_f32_dpp v161, v161, v161 quad_perm:[1,0,3,2] row_mask:0xf bank_mask:0xf bound_ctrl:1
	s_nop 0
	v_add_f32_dpp v160, v160, v160 quad_perm:[2,3,0,1] row_mask:0xf bank_mask:0xf bound_ctrl:1
	v_add_f32_dpp v161, v161, v161 quad_perm:[2,3,0,1] row_mask:0xf bank_mask:0xf bound_ctrl:1
	s_nop 0
	v_add_f32_dpp v160, v160, v160 row_half_mirror row_mask:0xf bank_mask:0xf bound_ctrl:1
	v_add_f32_dpp v161, v161, v161 row_half_mirror row_mask:0xf bank_mask:0xf bound_ctrl:1
	s_mov_b32 exec_lo, 0x01010101
	s_mov_b32 exec_hi, 0x01010101
	ds_write_b64 v1, v[160:161] offset:57856
	s_mov_b64 exec, -1
	s_add_i32 s3, s2, 1
	s_mov_b64 s[36:37], 0
